# select tail fast path (ballot+writelane when no surplus ties) and gate waves skip the unused LDS staging in phase A
# speedup vs baseline: 1.0299x; 1.0148x over previous
; template <int NJ>
; DI void b1_select(const float* sc, int nj, unsigned* mo) {
;     ...
;   int cgt = 0;
; #pragma unroll
;   for (int j = 0; j < NJ; ++j) cgt += __popcll(__ballot(key[j] > T));
;   const int need = 256 - cgt;
;   const unsigned long long lm = (1ull << lane) - 1ull;
;   int run = 0;
;   unsigned long long w0 = 0ull, w1 = 0ull;
; #pragma unroll
;   for (int j = 0; j < NJ; ++j) {
;     const bool e = key[j] == T;
;     const unsigned long long me = __ballot(e);
;     const int before = run + __popcll(me & lm);
;     const bool sel = (key[j] > T) || (e && before < need);
;     run += __popcll(me);
;     const unsigned long long ms = __ballot(sel);
;     if (j < 64) w0 = (lane == j) ? ms : w0; else w1 = (lane == j - 64) ? ms : w1;
;   }
;   if (NJ >= 64 || lane < NJ) *(u32x2*)(mo + 2 * lane) = u32x2{(unsigned)w0, (unsigned)(w0 >> 32)};
;   if (NJ > 64 && lane < NJ - 64) *(u32x2*)(mo + 128 + 2 * lane) = u32x2{(unsigned)w1, (unsigned)(w1 >> 32)};
.LBB0_511:
	s_mov_b32 s98, 0
	v_cmp_le_u32_e64 vcc, s97, v29
	v_cmp_le_u32_e64 s[100:101], s97, v5
	s_bcnt1_i32_b64 s99, vcc
	s_add_i32 s98, s98, s99
	v_writelane_b32 v212, vcc_lo, 0
	v_writelane_b32 v213, vcc_hi, 0
	v_cmp_le_u32_e64 vcc, s97, v2
	s_bcnt1_i32_b64 s99, s[100:101]
	s_add_i32 s98, s98, s99
	v_writelane_b32 v212, s100, 1
	v_writelane_b32 v213, s101, 1
	v_cmp_le_u32_e64 s[100:101], s97, v7
	s_bcnt1_i32_b64 s99, vcc
	s_add_i32 s98, s98, s99
	v_writelane_b32 v212, vcc_lo, 2
	v_writelane_b32 v213, vcc_hi, 2
	v_cmp_le_u32_e64 vcc, s97, v3
	s_bcnt1_i32_b64 s99, s[100:101]
	s_add_i32 s98, s98, s99
	v_writelane_b32 v212, s100, 3
	v_writelane_b32 v213, s101, 3
	v_cmp_le_u32_e64 s[100:101], s97, v9
	s_bcnt1_i32_b64 s99, vcc
	s_add_i32 s98, s98, s99
	v_writelane_b32 v212, vcc_lo, 4
	v_writelane_b32 v213, vcc_hi, 4
	v_cmp_le_u32_e64 vcc, s97, v4
	s_bcnt1_i32_b64 s99, s[100:101]
	s_add_i32 s98, s98, s99
	v_writelane_b32 v212, s100, 5
	v_writelane_b32 v213, s101, 5
	v_cmp_le_u32_e64 s[100:101], s97, v11
	s_bcnt1_i32_b64 s99, vcc
	s_add_i32 s98, s98, s99
	v_writelane_b32 v212, vcc_lo, 6
	v_writelane_b32 v213, vcc_hi, 6
	v_cmp_le_u32_e64 vcc, s97, v6
	s_bcnt1_i32_b64 s99, s[100:101]
	s_add_i32 s98, s98, s99
	v_writelane_b32 v212, s100, 7
	v_writelane_b32 v213, s101, 7
	v_cmp_le_u32_e64 s[100:101], s97, v13
	s_bcnt1_i32_b64 s99, vcc
	s_add_i32 s98, s98, s99
	v_writelane_b32 v212, vcc_lo, 8
	v_writelane_b32 v213, vcc_hi, 8
	v_cmp_le_u32_e64 vcc, s97, v8
	s_bcnt1_i32_b64 s99, s[100:101]
	s_add_i32 s98, s98, s99
	v_writelane_b32 v212, s100, 9
	v_writelane_b32 v213, s101, 9
	v_cmp_le_u32_e64 s[100:101], s97, v15
	s_bcnt1_i32_b64 s99, vcc
	s_add_i32 s98, s98, s99
	v_writelane_b32 v212, vcc_lo, 10
	v_writelane_b32 v213, vcc_hi, 10
	v_cmp_le_u32_e64 vcc, s97, v10
	s_bcnt1_i32_b64 s99, s[100:101]
	s_add_i32 s98, s98, s99
	v_writelane_b32 v212, s100, 11
	v_writelane_b32 v213, s101, 11
	v_cmp_le_u32_e64 s[100:101], s97, v17
	s_bcnt1_i32_b64 s99, vcc
	s_add_i32 s98, s98, s99
	v_writelane_b32 v212, vcc_lo, 12
	v_writelane_b32 v213, vcc_hi, 12
	v_cmp_le_u32_e64 vcc, s97, v12
	s_bcnt1_i32_b64 s99, s[100:101]
	s_add_i32 s98, s98, s99
	v_writelane_b32 v212, s100, 13
	v_writelane_b32 v213, s101, 13
	v_cmp_le_u32_e64 s[100:101], s97, v19
	s_bcnt1_i32_b64 s99, vcc
	s_add_i32 s98, s98, s99
	v_writelane_b32 v212, vcc_lo, 14
	v_writelane_b32 v213, vcc_hi, 14
	v_cmp_le_u32_e64 vcc, s97, v14
	s_bcnt1_i32_b64 s99, s[100:101]
	s_add_i32 s98, s98, s99
	v_writelane_b32 v212, s100, 15
	v_writelane_b32 v213, s101, 15
	v_cmp_le_u32_e64 s[100:101], s97, v21
	s_bcnt1_i32_b64 s99, vcc
	s_add_i32 s98, s98, s99
	v_writelane_b32 v212, vcc_lo, 16
	v_writelane_b32 v213, vcc_hi, 16
	v_cmp_le_u32_e64 vcc, s97, v16
	s_bcnt1_i32_b64 s99, s[100:101]
	s_add_i32 s98, s98, s99
	v_writelane_b32 v212, s100, 17
	v_writelane_b32 v213, s101, 17
	v_cmp_le_u32_e64 s[100:101], s97, v23
	s_bcnt1_i32_b64 s99, vcc
	s_add_i32 s98, s98, s99
	v_writelane_b32 v212, vcc_lo, 18
	v_writelane_b32 v213, vcc_hi, 18
	v_cmp_le_u32_e64 vcc, s97, v18
	s_bcnt1_i32_b64 s99, s[100:101]
	s_add_i32 s98, s98, s99
	v_writelane_b32 v212, s100, 19
	v_writelane_b32 v213, s101, 19
	v_cmp_le_u32_e64 s[100:101], s97, v25
	s_bcnt1_i32_b64 s99, vcc
	s_add_i32 s98, s98, s99
	v_writelane_b32 v212, vcc_lo, 20
	v_writelane_b32 v213, vcc_hi, 20
	v_cmp_le_u32_e64 vcc, s97, v20
	s_bcnt1_i32_b64 s99, s[100:101]
	s_add_i32 s98, s98, s99
	v_writelane_b32 v212, s100, 21
	v_writelane_b32 v213, s101, 21
	v_cmp_le_u32_e64 s[100:101], s97, v26
	s_bcnt1_i32_b64 s99, vcc
	s_add_i32 s98, s98, s99
	v_writelane_b32 v212, vcc_lo, 22
	v_writelane_b32 v213, vcc_hi, 22
	v_cmp_le_u32_e64 vcc, s97, v22
	s_bcnt1_i32_b64 s99, s[100:101]
	s_add_i32 s98, s98, s99
	v_writelane_b32 v212, s100, 23
	v_writelane_b32 v213, s101, 23
	v_cmp_le_u32_e64 s[100:101], s97, v27
	s_bcnt1_i32_b64 s99, vcc
	s_add_i32 s98, s98, s99
	v_writelane_b32 v212, vcc_lo, 24
	v_writelane_b32 v213, vcc_hi, 24
	v_cmp_le_u32_e64 vcc, s97, v24
	s_bcnt1_i32_b64 s99, s[100:101]
	s_add_i32 s98, s98, s99
	v_writelane_b32 v212, s100, 25
	v_writelane_b32 v213, s101, 25
	v_cmp_le_u32_e64 s[100:101], s97, v28
	s_bcnt1_i32_b64 s99, vcc
	s_add_i32 s98, s98, s99
	v_writelane_b32 v212, vcc_lo, 26
	v_writelane_b32 v213, vcc_hi, 26
	s_nop 0
	s_bcnt1_i32_b64 s99, s[100:101]
	s_add_i32 s98, s98, s99
	v_writelane_b32 v212, s100, 27
	v_writelane_b32 v213, s101, 27
	s_cmpk_lg_i32 s98, 0x100
	s_cbranch_scc1 .Lsf_slow_0
	v_cmp_gt_u32_e64 s[100:101], 28, v0
	s_and_saveexec_b64 s[60:61], s[100:101]
	v_lshlrev_b32_e32 v0, 3, v0
	v_readlane_b32 s0, v236, 9
	v_readlane_b32 s1, v236, 10
	s_nop 4
	global_store_dwordx2 v0, v[212:213], s[0:1]
	s_branch .LBB0_513

; template <int NJ>
; DI void b1_select(const float* sc, int nj, unsigned* mo) {
;     ...
;   int cgt = 0;
; #pragma unroll
;   for (int j = 0; j < NJ; ++j) cgt += __popcll(__ballot(key[j] > T));
;   const int need = 256 - cgt;
;   const unsigned long long lm = (1ull << lane) - 1ull;
;   int run = 0;
;   unsigned long long w0 = 0ull, w1 = 0ull;
; #pragma unroll
;   for (int j = 0; j < NJ; ++j) {
;     const bool e = key[j] == T;
;     const unsigned long long me = __ballot(e);
;     const int before = run + __popcll(me & lm);
;     const bool sel = (key[j] > T) || (e && before < need);
;     run += __popcll(me);
;     const unsigned long long ms = __ballot(sel);
;     if (j < 64) w0 = (lane == j) ? ms : w0; else w1 = (lane == j - 64) ? ms : w1;
;   }
;   if (NJ >= 64 || lane < NJ) *(u32x2*)(mo + 2 * lane) = u32x2{(unsigned)w0, (unsigned)(w0 >> 32)};
;   if (NJ > 64 && lane < NJ - 64) *(u32x2*)(mo + 128 + 2 * lane) = u32x2{(unsigned)w1, (unsigned)(w1 >> 32)};
.LBB0_576:
	s_mov_b32 s98, 0
	v_cmp_le_u32_e64 vcc, s60, v29
	v_cmp_le_u32_e64 s[100:101], s60, v5
	s_bcnt1_i32_b64 s99, vcc
	s_add_i32 s98, s98, s99
	v_writelane_b32 v212, vcc_lo, 0
	v_writelane_b32 v213, vcc_hi, 0
	v_cmp_le_u32_e64 vcc, s60, v2
	s_bcnt1_i32_b64 s99, s[100:101]
	s_add_i32 s98, s98, s99
	v_writelane_b32 v212, s100, 1
	v_writelane_b32 v213, s101, 1
	v_cmp_le_u32_e64 s[100:101], s60, v7
	s_bcnt1_i32_b64 s99, vcc
	s_add_i32 s98, s98, s99
	v_writelane_b32 v212, vcc_lo, 2
	v_writelane_b32 v213, vcc_hi, 2
	v_cmp_le_u32_e64 vcc, s60, v3
	s_bcnt1_i32_b64 s99, s[100:101]
	s_add_i32 s98, s98, s99
	v_writelane_b32 v212, s100, 3
	v_writelane_b32 v213, s101, 3
	v_cmp_le_u32_e64 s[100:101], s60, v9
	s_bcnt1_i32_b64 s99, vcc
	s_add_i32 s98, s98, s99
	v_writelane_b32 v212, vcc_lo, 4
	v_writelane_b32 v213, vcc_hi, 4
	v_cmp_le_u32_e64 vcc, s60, v4
	s_bcnt1_i32_b64 s99, s[100:101]
	s_add_i32 s98, s98, s99
	v_writelane_b32 v212, s100, 5
	v_writelane_b32 v213, s101, 5
	v_cmp_le_u32_e64 s[100:101], s60, v11
	s_bcnt1_i32_b64 s99, vcc
	s_add_i32 s98, s98, s99
	v_writelane_b32 v212, vcc_lo, 6
	v_writelane_b32 v213, vcc_hi, 6
	v_cmp_le_u32_e64 vcc, s60, v6
	s_bcnt1_i32_b64 s99, s[100:101]
	s_add_i32 s98, s98, s99
	v_writelane_b32 v212, s100, 7
	v_writelane_b32 v213, s101, 7
	v_cmp_le_u32_e64 s[100:101], s60, v13
	s_bcnt1_i32_b64 s99, vcc
	s_add_i32 s98, s98, s99
	v_writelane_b32 v212, vcc_lo, 8
	v_writelane_b32 v213, vcc_hi, 8
	v_cmp_le_u32_e64 vcc, s60, v8
	s_bcnt1_i32_b64 s99, s[100:101]
	s_add_i32 s98, s98, s99
	v_writelane_b32 v212, s100, 9
	v_writelane_b32 v213, s101, 9
	v_cmp_le_u32_e64 s[100:101], s60, v15
	s_bcnt1_i32_b64 s99, vcc
	s_add_i32 s98, s98, s99
	v_writelane_b32 v212, vcc_lo, 10
	v_writelane_b32 v213, vcc_hi, 10
	v_cmp_le_u32_e64 vcc, s60, v10
	s_bcnt1_i32_b64 s99, s[100:101]
	s_add_i32 s98, s98, s99
	v_writelane_b32 v212, s100, 11
	v_writelane_b32 v213, s101, 11
	v_cmp_le_u32_e64 s[100:101], s60, v17
	s_bcnt1_i32_b64 s99, vcc
	s_add_i32 s98, s98, s99
	v_writelane_b32 v212, vcc_lo, 12
	v_writelane_b32 v213, vcc_hi, 12
	v_cmp_le_u32_e64 vcc, s60, v12
	s_bcnt1_i32_b64 s99, s[100:101]
	s_add_i32 s98, s98, s99
	v_writelane_b32 v212, s100, 13
	v_writelane_b32 v213, s101, 13
	v_cmp_le_u32_e64 s[100:101], s60, v19
	s_bcnt1_i32_b64 s99, vcc
	s_add_i32 s98, s98, s99
	v_writelane_b32 v212, vcc_lo, 14
	v_writelane_b32 v213, vcc_hi, 14
	v_cmp_le_u32_e64 vcc, s60, v14
	s_bcnt1_i32_b64 s99, s[100:101]
	s_add_i32 s98, s98, s99
	v_writelane_b32 v212, s100, 15
	v_writelane_b32 v213, s101, 15
	v_cmp_le_u32_e64 s[100:101], s60, v21
	s_bcnt1_i32_b64 s99, vcc
	s_add_i32 s98, s98, s99
	v_writelane_b32 v212, vcc_lo, 16
	v_writelane_b32 v213, vcc_hi, 16
	v_cmp_le_u32_e64 vcc, s60, v16
	s_bcnt1_i32_b64 s99, s[100:101]
	s_add_i32 s98, s98, s99
	v_writelane_b32 v212, s100, 17
	v_writelane_b32 v213, s101, 17
	v_cmp_le_u32_e64 s[100:101], s60, v23
	s_bcnt1_i32_b64 s99, vcc
	s_add_i32 s98, s98, s99
	v_writelane_b32 v212, vcc_lo, 18
	v_writelane_b32 v213, vcc_hi, 18
	v_cmp_le_u32_e64 vcc, s60, v18
	s_bcnt1_i32_b64 s99, s[100:101]
	s_add_i32 s98, s98, s99
	v_writelane_b32 v212, s100, 19
	v_writelane_b32 v213, s101, 19
	v_cmp_le_u32_e64 s[100:101], s60, v25
	s_bcnt1_i32_b64 s99, vcc
	s_add_i32 s98, s98, s99
	v_writelane_b32 v212, vcc_lo, 20
	v_writelane_b32 v213, vcc_hi, 20
	v_cmp_le_u32_e64 vcc, s60, v20
	s_bcnt1_i32_b64 s99, s[100:101]
	s_add_i32 s98, s98, s99
	v_writelane_b32 v212, s100, 21
	v_writelane_b32 v213, s101, 21
	v_cmp_le_u32_e64 s[100:101], s60, v26
	s_bcnt1_i32_b64 s99, vcc
	s_add_i32 s98, s98, s99
	v_writelane_b32 v212, vcc_lo, 22
	v_writelane_b32 v213, vcc_hi, 22
	v_cmp_le_u32_e64 vcc, s60, v22
	s_bcnt1_i32_b64 s99, s[100:101]
	s_add_i32 s98, s98, s99
	v_writelane_b32 v212, s100, 23
	v_writelane_b32 v213, s101, 23
	v_cmp_le_u32_e64 s[100:101], s60, v28
	s_bcnt1_i32_b64 s99, vcc
	s_add_i32 s98, s98, s99
	v_writelane_b32 v212, vcc_lo, 24
	v_writelane_b32 v213, vcc_hi, 24
	v_cmp_le_u32_e64 vcc, s60, v24
	s_bcnt1_i32_b64 s99, s[100:101]
	s_add_i32 s98, s98, s99
	v_writelane_b32 v212, s100, 25
	v_writelane_b32 v213, s101, 25
	v_cmp_le_u32_e64 s[100:101], s60, v27
	s_bcnt1_i32_b64 s99, vcc
	s_add_i32 s98, s98, s99
	v_writelane_b32 v212, vcc_lo, 26
	v_writelane_b32 v213, vcc_hi, 26
	s_nop 0
	s_bcnt1_i32_b64 s99, s[100:101]
	s_add_i32 s98, s98, s99
	v_writelane_b32 v212, s100, 27
	v_writelane_b32 v213, s101, 27
	s_cmpk_lg_i32 s98, 0x100
	s_cbranch_scc1 .Lsf_slow_1
	v_cmp_gt_u32_e64 s[100:101], 28, v0
	s_and_saveexec_b64 s[58:59], s[100:101]
	v_lshlrev_b32_e32 v0, 3, v0
	v_readlane_b32 s0, v236, 9
	v_readlane_b32 s1, v236, 10
	s_nop 4
	global_store_dwordx2 v0, v[212:213], s[0:1] offset:256
	s_branch .LBB0_578

; template <int NJ>
; DI void b1_select(const float* sc, int nj, unsigned* mo) {
;     ...
;   int cgt = 0;
; #pragma unroll
;   for (int j = 0; j < NJ; ++j) cgt += __popcll(__ballot(key[j] > T));
;   const int need = 256 - cgt;
;   const unsigned long long lm = (1ull << lane) - 1ull;
;   int run = 0;
;   unsigned long long w0 = 0ull, w1 = 0ull;
; #pragma unroll
;   for (int j = 0; j < NJ; ++j) {
;     const bool e = key[j] == T;
;     const unsigned long long me = __ballot(e);
;     const int before = run + __popcll(me & lm);
;     const bool sel = (key[j] > T) || (e && before < need);
;     run += __popcll(me);
;     const unsigned long long ms = __ballot(sel);
;     if (j < 64) w0 = (lane == j) ? ms : w0; else w1 = (lane == j - 64) ? ms : w1;
;   }
;   if (NJ >= 64 || lane < NJ) *(u32x2*)(mo + 2 * lane) = u32x2{(unsigned)w0, (unsigned)(w0 >> 32)};
;   if (NJ > 64 && lane < NJ - 64) *(u32x2*)(mo + 128 + 2 * lane) = u32x2{(unsigned)w1, (unsigned)(w1 >> 32)};
.LBB0_636:
	s_mov_b32 s98, 0
	v_cmp_le_u32_e64 vcc, s94, v25
	v_cmp_le_u32_e64 s[100:101], s94, v5
	s_bcnt1_i32_b64 s99, vcc
	s_add_i32 s98, s98, s99
	v_writelane_b32 v212, vcc_lo, 0
	v_writelane_b32 v213, vcc_hi, 0
	v_cmp_le_u32_e64 vcc, s94, v2
	s_bcnt1_i32_b64 s99, s[100:101]
	s_add_i32 s98, s98, s99
	v_writelane_b32 v212, s100, 1
	v_writelane_b32 v213, s101, 1
	v_cmp_le_u32_e64 s[100:101], s94, v7
	s_bcnt1_i32_b64 s99, vcc
	s_add_i32 s98, s98, s99
	v_writelane_b32 v212, vcc_lo, 2
	v_writelane_b32 v213, vcc_hi, 2
	v_cmp_le_u32_e64 vcc, s94, v3
	s_bcnt1_i32_b64 s99, s[100:101]
	s_add_i32 s98, s98, s99
	v_writelane_b32 v212, s100, 3
	v_writelane_b32 v213, s101, 3
	v_cmp_le_u32_e64 s[100:101], s94, v9
	s_bcnt1_i32_b64 s99, vcc
	s_add_i32 s98, s98, s99
	v_writelane_b32 v212, vcc_lo, 4
	v_writelane_b32 v213, vcc_hi, 4
	v_cmp_le_u32_e64 vcc, s94, v4
	s_bcnt1_i32_b64 s99, s[100:101]
	s_add_i32 s98, s98, s99
	v_writelane_b32 v212, s100, 5
	v_writelane_b32 v213, s101, 5
	v_cmp_le_u32_e64 s[100:101], s94, v11
	s_bcnt1_i32_b64 s99, vcc
	s_add_i32 s98, s98, s99
	v_writelane_b32 v212, vcc_lo, 6
	v_writelane_b32 v213, vcc_hi, 6
	v_cmp_le_u32_e64 vcc, s94, v6
	s_bcnt1_i32_b64 s99, s[100:101]
	s_add_i32 s98, s98, s99
	v_writelane_b32 v212, s100, 7
	v_writelane_b32 v213, s101, 7
	v_cmp_le_u32_e64 s[100:101], s94, v13
	s_bcnt1_i32_b64 s99, vcc
	s_add_i32 s98, s98, s99
	v_writelane_b32 v212, vcc_lo, 8
	v_writelane_b32 v213, vcc_hi, 8
	v_cmp_le_u32_e64 vcc, s94, v8
	s_bcnt1_i32_b64 s99, s[100:101]
	s_add_i32 s98, s98, s99
	v_writelane_b32 v212, s100, 9
	v_writelane_b32 v213, s101, 9
	v_cmp_le_u32_e64 s[100:101], s94, v15
	s_bcnt1_i32_b64 s99, vcc
	s_add_i32 s98, s98, s99
	v_writelane_b32 v212, vcc_lo, 10
	v_writelane_b32 v213, vcc_hi, 10
	v_cmp_le_u32_e64 vcc, s94, v10
	s_bcnt1_i32_b64 s99, s[100:101]
	s_add_i32 s98, s98, s99
	v_writelane_b32 v212, s100, 11
	v_writelane_b32 v213, s101, 11
	v_cmp_le_u32_e64 s[100:101], s94, v17
	s_bcnt1_i32_b64 s99, vcc
	s_add_i32 s98, s98, s99
	v_writelane_b32 v212, vcc_lo, 12
	v_writelane_b32 v213, vcc_hi, 12
	v_cmp_le_u32_e64 vcc, s94, v12
	s_bcnt1_i32_b64 s99, s[100:101]
	s_add_i32 s98, s98, s99
	v_writelane_b32 v212, s100, 13
	v_writelane_b32 v213, s101, 13
	v_cmp_le_u32_e64 s[100:101], s94, v19
	s_bcnt1_i32_b64 s99, vcc
	s_add_i32 s98, s98, s99
	v_writelane_b32 v212, vcc_lo, 14
	v_writelane_b32 v213, vcc_hi, 14
	v_cmp_le_u32_e64 vcc, s94, v14
	s_bcnt1_i32_b64 s99, s[100:101]
	s_add_i32 s98, s98, s99
	v_writelane_b32 v212, s100, 15
	v_writelane_b32 v213, s101, 15
	v_cmp_le_u32_e64 s[100:101], s94, v21
	s_bcnt1_i32_b64 s99, vcc
	s_add_i32 s98, s98, s99
	v_writelane_b32 v212, vcc_lo, 16
	v_writelane_b32 v213, vcc_hi, 16
	v_cmp_le_u32_e64 vcc, s94, v16
	s_bcnt1_i32_b64 s99, s[100:101]
	s_add_i32 s98, s98, s99
	v_writelane_b32 v212, s100, 17
	v_writelane_b32 v213, s101, 17
	v_cmp_le_u32_e64 s[100:101], s94, v22
	s_bcnt1_i32_b64 s99, vcc
	s_add_i32 s98, s98, s99
	v_writelane_b32 v212, vcc_lo, 18
	v_writelane_b32 v213, vcc_hi, 18
	v_cmp_le_u32_e64 vcc, s94, v18
	s_bcnt1_i32_b64 s99, s[100:101]
	s_add_i32 s98, s98, s99
	v_writelane_b32 v212, s100, 19
	v_writelane_b32 v213, s101, 19
	v_cmp_le_u32_e64 s[100:101], s94, v23
	s_bcnt1_i32_b64 s99, vcc
	s_add_i32 s98, s98, s99
	v_writelane_b32 v212, vcc_lo, 20
	v_writelane_b32 v213, vcc_hi, 20
	v_cmp_le_u32_e64 vcc, s94, v20
	s_bcnt1_i32_b64 s99, s[100:101]
	s_add_i32 s98, s98, s99
	v_writelane_b32 v212, s100, 21
	v_writelane_b32 v213, s101, 21
	v_cmp_le_u32_e64 s[100:101], s94, v24
	s_bcnt1_i32_b64 s99, vcc
	s_add_i32 s98, s98, s99
	v_writelane_b32 v212, vcc_lo, 22
	v_writelane_b32 v213, vcc_hi, 22
	s_nop 0
	s_bcnt1_i32_b64 s99, s[100:101]
	s_add_i32 s98, s98, s99
	v_writelane_b32 v212, s100, 23
	v_writelane_b32 v213, s101, 23
	s_cmpk_lg_i32 s98, 0x100
	s_cbranch_scc1 .Lsf_slow_2
	v_cmp_gt_u32_e64 s[100:101], 24, v0
	s_and_saveexec_b64 s[52:53], s[100:101]
	v_lshlrev_b32_e32 v0, 3, v0
	v_readlane_b32 s0, v236, 9
	v_readlane_b32 s1, v236, 10
	s_nop 4
	global_store_dwordx2 v0, v[212:213], s[0:1]
	s_branch .LBB0_638

; template <int NJ>
; DI void b1_select(const float* sc, int nj, unsigned* mo) {
;     ...
;   int cgt = 0;
; #pragma unroll
;   for (int j = 0; j < NJ; ++j) cgt += __popcll(__ballot(key[j] > T));
;   const int need = 256 - cgt;
;   const unsigned long long lm = (1ull << lane) - 1ull;
;   int run = 0;
;   unsigned long long w0 = 0ull, w1 = 0ull;
; #pragma unroll
;   for (int j = 0; j < NJ; ++j) {
;     const bool e = key[j] == T;
;     const unsigned long long me = __ballot(e);
;     const int before = run + __popcll(me & lm);
;     const bool sel = (key[j] > T) || (e && before < need);
;     run += __popcll(me);
;     const unsigned long long ms = __ballot(sel);
;     if (j < 64) w0 = (lane == j) ? ms : w0; else w1 = (lane == j - 64) ? ms : w1;
;   }
;   if (NJ >= 64 || lane < NJ) *(u32x2*)(mo + 2 * lane) = u32x2{(unsigned)w0, (unsigned)(w0 >> 32)};
;   if (NJ > 64 && lane < NJ - 64) *(u32x2*)(mo + 128 + 2 * lane) = u32x2{(unsigned)w1, (unsigned)(w1 >> 32)};
.LBB0_693:
	s_mov_b32 s98, 0
	v_cmp_le_u32_e64 vcc, s52, v25
	v_cmp_le_u32_e64 s[100:101], s52, v3
	s_bcnt1_i32_b64 s99, vcc
	s_add_i32 s98, s98, s99
	v_writelane_b32 v212, vcc_lo, 0
	v_writelane_b32 v213, vcc_hi, 0
	v_cmp_le_u32_e64 vcc, s52, v2
	s_bcnt1_i32_b64 s99, s[100:101]
	s_add_i32 s98, s98, s99
	v_writelane_b32 v212, s100, 1
	v_writelane_b32 v213, s101, 1
	v_cmp_le_u32_e64 s[100:101], s52, v7
	s_bcnt1_i32_b64 s99, vcc
	s_add_i32 s98, s98, s99
	v_writelane_b32 v212, vcc_lo, 2
	v_writelane_b32 v213, vcc_hi, 2
	v_cmp_le_u32_e64 vcc, s52, v4
	s_bcnt1_i32_b64 s99, s[100:101]
	s_add_i32 s98, s98, s99
	v_writelane_b32 v212, s100, 3
	v_writelane_b32 v213, s101, 3
	v_cmp_le_u32_e64 s[100:101], s52, v9
	s_bcnt1_i32_b64 s99, vcc
	s_add_i32 s98, s98, s99
	v_writelane_b32 v212, vcc_lo, 4
	v_writelane_b32 v213, vcc_hi, 4
	v_cmp_le_u32_e64 vcc, s52, v5
	s_bcnt1_i32_b64 s99, s[100:101]
	s_add_i32 s98, s98, s99
	v_writelane_b32 v212, s100, 5
	v_writelane_b32 v213, s101, 5
	v_cmp_le_u32_e64 s[100:101], s52, v11
	s_bcnt1_i32_b64 s99, vcc
	s_add_i32 s98, s98, s99
	v_writelane_b32 v212, vcc_lo, 6
	v_writelane_b32 v213, vcc_hi, 6
	v_cmp_le_u32_e64 vcc, s52, v6
	s_bcnt1_i32_b64 s99, s[100:101]
	s_add_i32 s98, s98, s99
	v_writelane_b32 v212, s100, 7
	v_writelane_b32 v213, s101, 7
	v_cmp_le_u32_e64 s[100:101], s52, v13
	s_bcnt1_i32_b64 s99, vcc
	s_add_i32 s98, s98, s99
	v_writelane_b32 v212, vcc_lo, 8
	v_writelane_b32 v213, vcc_hi, 8
	v_cmp_le_u32_e64 vcc, s52, v8
	s_bcnt1_i32_b64 s99, s[100:101]
	s_add_i32 s98, s98, s99
	v_writelane_b32 v212, s100, 9
	v_writelane_b32 v213, s101, 9
	v_cmp_le_u32_e64 s[100:101], s52, v15
	s_bcnt1_i32_b64 s99, vcc
	s_add_i32 s98, s98, s99
	v_writelane_b32 v212, vcc_lo, 10
	v_writelane_b32 v213, vcc_hi, 10
	v_cmp_le_u32_e64 vcc, s52, v10
	s_bcnt1_i32_b64 s99, s[100:101]
	s_add_i32 s98, s98, s99
	v_writelane_b32 v212, s100, 11
	v_writelane_b32 v213, s101, 11
	v_cmp_le_u32_e64 s[100:101], s52, v17
	s_bcnt1_i32_b64 s99, vcc
	s_add_i32 s98, s98, s99
	v_writelane_b32 v212, vcc_lo, 12
	v_writelane_b32 v213, vcc_hi, 12
	v_cmp_le_u32_e64 vcc, s52, v12
	s_bcnt1_i32_b64 s99, s[100:101]
	s_add_i32 s98, s98, s99
	v_writelane_b32 v212, s100, 13
	v_writelane_b32 v213, s101, 13
	v_cmp_le_u32_e64 s[100:101], s52, v19
	s_bcnt1_i32_b64 s99, vcc
	s_add_i32 s98, s98, s99
	v_writelane_b32 v212, vcc_lo, 14
	v_writelane_b32 v213, vcc_hi, 14
	v_cmp_le_u32_e64 vcc, s52, v14
	s_bcnt1_i32_b64 s99, s[100:101]
	s_add_i32 s98, s98, s99
	v_writelane_b32 v212, s100, 15
	v_writelane_b32 v213, s101, 15
	v_cmp_le_u32_e64 s[100:101], s52, v21
	s_bcnt1_i32_b64 s99, vcc
	s_add_i32 s98, s98, s99
	v_writelane_b32 v212, vcc_lo, 16
	v_writelane_b32 v213, vcc_hi, 16
	v_cmp_le_u32_e64 vcc, s52, v16
	s_bcnt1_i32_b64 s99, s[100:101]
	s_add_i32 s98, s98, s99
	v_writelane_b32 v212, s100, 17
	v_writelane_b32 v213, s101, 17
	v_cmp_le_u32_e64 s[100:101], s52, v22
	s_bcnt1_i32_b64 s99, vcc
	s_add_i32 s98, s98, s99
	v_writelane_b32 v212, vcc_lo, 18
	v_writelane_b32 v213, vcc_hi, 18
	v_cmp_le_u32_e64 vcc, s52, v18
	s_bcnt1_i32_b64 s99, s[100:101]
	s_add_i32 s98, s98, s99
	v_writelane_b32 v212, s100, 19
	v_writelane_b32 v213, s101, 19
	v_cmp_le_u32_e64 s[100:101], s52, v23
	s_bcnt1_i32_b64 s99, vcc
	s_add_i32 s98, s98, s99
	v_writelane_b32 v212, vcc_lo, 20
	v_writelane_b32 v213, vcc_hi, 20
	v_cmp_le_u32_e64 vcc, s52, v20
	s_bcnt1_i32_b64 s99, s[100:101]
	s_add_i32 s98, s98, s99
	v_writelane_b32 v212, s100, 21
	v_writelane_b32 v213, s101, 21
	v_cmp_le_u32_e64 s[100:101], s52, v24
	s_bcnt1_i32_b64 s99, vcc
	s_add_i32 s98, s98, s99
	v_writelane_b32 v212, vcc_lo, 22
	v_writelane_b32 v213, vcc_hi, 22
	s_nop 0
	s_bcnt1_i32_b64 s99, s[100:101]
	s_add_i32 s98, s98, s99
	v_writelane_b32 v212, s100, 23
	v_writelane_b32 v213, s101, 23
	s_cmpk_lg_i32 s98, 0x100
	s_cbranch_scc1 .Lsf_slow_3
	v_cmp_gt_u32_e64 s[100:101], 24, v0
	s_and_saveexec_b64 s[50:51], s[100:101]
	v_lshlrev_b32_e32 v0, 3, v0
	v_readlane_b32 s0, v236, 9
	v_readlane_b32 s1, v236, 10
	s_nop 4
	global_store_dwordx2 v0, v[212:213], s[0:1] offset:256
	s_branch .LBB0_695

; template <int NJ>
; DI void b1_select(const float* sc, int nj, unsigned* mo) {
;     ...
;   int cgt = 0;
; #pragma unroll
;   for (int j = 0; j < NJ; ++j) cgt += __popcll(__ballot(key[j] > T));
;   const int need = 256 - cgt;
;   const unsigned long long lm = (1ull << lane) - 1ull;
;   int run = 0;
;   unsigned long long w0 = 0ull, w1 = 0ull;
; #pragma unroll
;   for (int j = 0; j < NJ; ++j) {
;     const bool e = key[j] == T;
;     const unsigned long long me = __ballot(e);
;     const int before = run + __popcll(me & lm);
;     const bool sel = (key[j] > T) || (e && before < need);
;     run += __popcll(me);
;     const unsigned long long ms = __ballot(sel);
;     if (j < 64) w0 = (lane == j) ? ms : w0; else w1 = (lane == j - 64) ? ms : w1;
;   }
;   if (NJ >= 64 || lane < NJ) *(u32x2*)(mo + 2 * lane) = u32x2{(unsigned)w0, (unsigned)(w0 >> 32)};
;   if (NJ > 64 && lane < NJ - 64) *(u32x2*)(mo + 128 + 2 * lane) = u32x2{(unsigned)w1, (unsigned)(w1 >> 32)};
.LBB0_745:
	s_mov_b32 s98, 0
	v_cmp_le_u32_e64 vcc, s97, v21
	v_cmp_le_u32_e64 s[100:101], s97, v4
	s_bcnt1_i32_b64 s99, vcc
	s_add_i32 s98, s98, s99
	v_writelane_b32 v212, vcc_lo, 0
	v_writelane_b32 v213, vcc_hi, 0
	v_cmp_le_u32_e64 vcc, s97, v2
	s_bcnt1_i32_b64 s99, s[100:101]
	s_add_i32 s98, s98, s99
	v_writelane_b32 v212, s100, 1
	v_writelane_b32 v213, s101, 1
	v_cmp_le_u32_e64 s[100:101], s97, v7
	s_bcnt1_i32_b64 s99, vcc
	s_add_i32 s98, s98, s99
	v_writelane_b32 v212, vcc_lo, 2
	v_writelane_b32 v213, vcc_hi, 2
	v_cmp_le_u32_e64 vcc, s97, v3
	s_bcnt1_i32_b64 s99, s[100:101]
	s_add_i32 s98, s98, s99
	v_writelane_b32 v212, s100, 3
	v_writelane_b32 v213, s101, 3
	v_cmp_le_u32_e64 s[100:101], s97, v9
	s_bcnt1_i32_b64 s99, vcc
	s_add_i32 s98, s98, s99
	v_writelane_b32 v212, vcc_lo, 4
	v_writelane_b32 v213, vcc_hi, 4
	v_cmp_le_u32_e64 vcc, s97, v5
	s_bcnt1_i32_b64 s99, s[100:101]
	s_add_i32 s98, s98, s99
	v_writelane_b32 v212, s100, 5
	v_writelane_b32 v213, s101, 5
	v_cmp_le_u32_e64 s[100:101], s97, v10
	s_bcnt1_i32_b64 s99, vcc
	s_add_i32 s98, s98, s99
	v_writelane_b32 v212, vcc_lo, 6
	v_writelane_b32 v213, vcc_hi, 6
	v_cmp_le_u32_e64 vcc, s97, v6
	s_bcnt1_i32_b64 s99, s[100:101]
	s_add_i32 s98, s98, s99
	v_writelane_b32 v212, s100, 7
	v_writelane_b32 v213, s101, 7
	v_cmp_le_u32_e64 s[100:101], s97, v12
	s_bcnt1_i32_b64 s99, vcc
	s_add_i32 s98, s98, s99
	v_writelane_b32 v212, vcc_lo, 8
	v_writelane_b32 v213, vcc_hi, 8
	v_cmp_le_u32_e64 vcc, s97, v8
	s_bcnt1_i32_b64 s99, s[100:101]
	s_add_i32 s98, s98, s99
	v_writelane_b32 v212, s100, 9
	v_writelane_b32 v213, s101, 9
	v_cmp_le_u32_e64 s[100:101], s97, v15
	s_bcnt1_i32_b64 s99, vcc
	s_add_i32 s98, s98, s99
	v_writelane_b32 v212, vcc_lo, 10
	v_writelane_b32 v213, vcc_hi, 10
	v_cmp_le_u32_e64 vcc, s97, v11
	s_bcnt1_i32_b64 s99, s[100:101]
	s_add_i32 s98, s98, s99
	v_writelane_b32 v212, s100, 11
	v_writelane_b32 v213, s101, 11
	v_cmp_le_u32_e64 s[100:101], s97, v17
	s_bcnt1_i32_b64 s99, vcc
	s_add_i32 s98, s98, s99
	v_writelane_b32 v212, vcc_lo, 12
	v_writelane_b32 v213, vcc_hi, 12
	v_cmp_le_u32_e64 vcc, s97, v13
	s_bcnt1_i32_b64 s99, s[100:101]
	s_add_i32 s98, s98, s99
	v_writelane_b32 v212, s100, 13
	v_writelane_b32 v213, s101, 13
	v_cmp_le_u32_e64 s[100:101], s97, v18
	s_bcnt1_i32_b64 s99, vcc
	s_add_i32 s98, s98, s99
	v_writelane_b32 v212, vcc_lo, 14
	v_writelane_b32 v213, vcc_hi, 14
	v_cmp_le_u32_e64 vcc, s97, v14
	s_bcnt1_i32_b64 s99, s[100:101]
	s_add_i32 s98, s98, s99
	v_writelane_b32 v212, s100, 15
	v_writelane_b32 v213, s101, 15
	v_cmp_le_u32_e64 s[100:101], s97, v19
	s_bcnt1_i32_b64 s99, vcc
	s_add_i32 s98, s98, s99
	v_writelane_b32 v212, vcc_lo, 16
	v_writelane_b32 v213, vcc_hi, 16
	v_cmp_le_u32_e64 vcc, s97, v16
	s_bcnt1_i32_b64 s99, s[100:101]
	s_add_i32 s98, s98, s99
	v_writelane_b32 v212, s100, 17
	v_writelane_b32 v213, s101, 17
	v_cmp_le_u32_e64 s[100:101], s97, v20
	s_bcnt1_i32_b64 s99, vcc
	s_add_i32 s98, s98, s99
	v_writelane_b32 v212, vcc_lo, 18
	v_writelane_b32 v213, vcc_hi, 18
	s_nop 0
	s_bcnt1_i32_b64 s99, s[100:101]
	s_add_i32 s98, s98, s99
	v_writelane_b32 v212, s100, 19
	v_writelane_b32 v213, s101, 19
	s_cmpk_lg_i32 s98, 0x100
	s_cbranch_scc1 .Lsf_slow_4
	s_mov_b32 s57, s72
	v_cmp_gt_u32_e64 s[100:101], 20, v0
	s_and_saveexec_b64 s[44:45], s[100:101]
	v_lshlrev_b32_e32 v0, 3, v0
	v_readlane_b32 s0, v236, 9
	v_readlane_b32 s1, v236, 10
	s_nop 4
	global_store_dwordx2 v0, v[212:213], s[0:1]
	s_branch .LBB0_747

; template <int NJ>
; DI void b1_select(const float* sc, int nj, unsigned* mo) {
;     ...
;   int cgt = 0;
; #pragma unroll
;   for (int j = 0; j < NJ; ++j) cgt += __popcll(__ballot(key[j] > T));
;   const int need = 256 - cgt;
;   const unsigned long long lm = (1ull << lane) - 1ull;
;   int run = 0;
;   unsigned long long w0 = 0ull, w1 = 0ull;
; #pragma unroll
;   for (int j = 0; j < NJ; ++j) {
;     const bool e = key[j] == T;
;     const unsigned long long me = __ballot(e);
;     const int before = run + __popcll(me & lm);
;     const bool sel = (key[j] > T) || (e && before < need);
;     run += __popcll(me);
;     const unsigned long long ms = __ballot(sel);
;     if (j < 64) w0 = (lane == j) ? ms : w0; else w1 = (lane == j - 64) ? ms : w1;
;   }
;   if (NJ >= 64 || lane < NJ) *(u32x2*)(mo + 2 * lane) = u32x2{(unsigned)w0, (unsigned)(w0 >> 32)};
;   if (NJ > 64 && lane < NJ - 64) *(u32x2*)(mo + 128 + 2 * lane) = u32x2{(unsigned)w1, (unsigned)(w1 >> 32)};
.LBB0_794:
	s_mov_b32 s98, 0
	v_cmp_le_u32_e64 vcc, s44, v21
	v_cmp_le_u32_e64 s[100:101], s44, v4
	s_bcnt1_i32_b64 s99, vcc
	s_add_i32 s98, s98, s99
	v_writelane_b32 v212, vcc_lo, 0
	v_writelane_b32 v213, vcc_hi, 0
	v_cmp_le_u32_e64 vcc, s44, v2
	s_bcnt1_i32_b64 s99, s[100:101]
	s_add_i32 s98, s98, s99
	v_writelane_b32 v212, s100, 1
	v_writelane_b32 v213, s101, 1
	v_cmp_le_u32_e64 s[100:101], s44, v8
	s_bcnt1_i32_b64 s99, vcc
	s_add_i32 s98, s98, s99
	v_writelane_b32 v212, vcc_lo, 2
	v_writelane_b32 v213, vcc_hi, 2
	v_cmp_le_u32_e64 vcc, s44, v3
	s_bcnt1_i32_b64 s99, s[100:101]
	s_add_i32 s98, s98, s99
	v_writelane_b32 v212, s100, 3
	v_writelane_b32 v213, s101, 3
	v_cmp_le_u32_e64 s[100:101], s44, v9
	s_bcnt1_i32_b64 s99, vcc
	s_add_i32 s98, s98, s99
	v_writelane_b32 v212, vcc_lo, 4
	v_writelane_b32 v213, vcc_hi, 4
	v_cmp_le_u32_e64 vcc, s44, v5
	s_bcnt1_i32_b64 s99, s[100:101]
	s_add_i32 s98, s98, s99
	v_writelane_b32 v212, s100, 5
	v_writelane_b32 v213, s101, 5
	v_cmp_le_u32_e64 s[100:101], s44, v11
	s_bcnt1_i32_b64 s99, vcc
	s_add_i32 s98, s98, s99
	v_writelane_b32 v212, vcc_lo, 6
	v_writelane_b32 v213, vcc_hi, 6
	v_cmp_le_u32_e64 vcc, s44, v6
	s_bcnt1_i32_b64 s99, s[100:101]
	s_add_i32 s98, s98, s99
	v_writelane_b32 v212, s100, 7
	v_writelane_b32 v213, s101, 7
	v_cmp_le_u32_e64 s[100:101], s44, v12
	s_bcnt1_i32_b64 s99, vcc
	s_add_i32 s98, s98, s99
	v_writelane_b32 v212, vcc_lo, 8
	v_writelane_b32 v213, vcc_hi, 8
	v_cmp_le_u32_e64 vcc, s44, v7
	s_bcnt1_i32_b64 s99, s[100:101]
	s_add_i32 s98, s98, s99
	v_writelane_b32 v212, s100, 9
	v_writelane_b32 v213, s101, 9
	v_cmp_le_u32_e64 s[100:101], s44, v14
	s_bcnt1_i32_b64 s99, vcc
	s_add_i32 s98, s98, s99
	v_writelane_b32 v212, vcc_lo, 10
	v_writelane_b32 v213, vcc_hi, 10
	v_cmp_le_u32_e64 vcc, s44, v10
	s_bcnt1_i32_b64 s99, s[100:101]
	s_add_i32 s98, s98, s99
	v_writelane_b32 v212, s100, 11
	v_writelane_b32 v213, s101, 11
	v_cmp_le_u32_e64 s[100:101], s44, v16
	s_bcnt1_i32_b64 s99, vcc
	s_add_i32 s98, s98, s99
	v_writelane_b32 v212, vcc_lo, 12
	v_writelane_b32 v213, vcc_hi, 12
	v_cmp_le_u32_e64 vcc, s44, v13
	s_bcnt1_i32_b64 s99, s[100:101]
	s_add_i32 s98, s98, s99
	v_writelane_b32 v212, s100, 13
	v_writelane_b32 v213, s101, 13
	v_cmp_le_u32_e64 s[100:101], s44, v18
	s_bcnt1_i32_b64 s99, vcc
	s_add_i32 s98, s98, s99
	v_writelane_b32 v212, vcc_lo, 14
	v_writelane_b32 v213, vcc_hi, 14
	v_cmp_le_u32_e64 vcc, s44, v15
	s_bcnt1_i32_b64 s99, s[100:101]
	s_add_i32 s98, s98, s99
	v_writelane_b32 v212, s100, 15
	v_writelane_b32 v213, s101, 15
	v_cmp_le_u32_e64 s[100:101], s44, v19
	s_bcnt1_i32_b64 s99, vcc
	s_add_i32 s98, s98, s99
	v_writelane_b32 v212, vcc_lo, 16
	v_writelane_b32 v213, vcc_hi, 16
	v_cmp_le_u32_e64 vcc, s44, v17
	s_bcnt1_i32_b64 s99, s[100:101]
	s_add_i32 s98, s98, s99
	v_writelane_b32 v212, s100, 17
	v_writelane_b32 v213, s101, 17
	v_cmp_le_u32_e64 s[100:101], s44, v20
	s_bcnt1_i32_b64 s99, vcc
	s_add_i32 s98, s98, s99
	v_writelane_b32 v212, vcc_lo, 18
	v_writelane_b32 v213, vcc_hi, 18
	s_nop 0
	s_bcnt1_i32_b64 s99, s[100:101]
	s_add_i32 s98, s98, s99
	v_writelane_b32 v212, s100, 19
	v_writelane_b32 v213, s101, 19
	s_cmpk_lg_i32 s98, 0x100
	s_cbranch_scc1 .Lsf_slow_5
	s_mov_b64 s[62:63], s[12:13]
	v_cmp_gt_u32_e64 s[100:101], 20, v0
	s_and_saveexec_b64 s[42:43], s[100:101]
	v_lshlrev_b32_e32 v0, 3, v0
	v_readlane_b32 s0, v236, 9
	v_readlane_b32 s1, v236, 10
	s_nop 4
	global_store_dwordx2 v0, v[212:213], s[0:1] offset:256
	s_branch .LBB0_796

; template <int NJ>
; DI void b1_select(const float* sc, int nj, unsigned* mo) {
;     ...
;   int cgt = 0;
; #pragma unroll
;   for (int j = 0; j < NJ; ++j) cgt += __popcll(__ballot(key[j] > T));
;   const int need = 256 - cgt;
;   const unsigned long long lm = (1ull << lane) - 1ull;
;   int run = 0;
;   unsigned long long w0 = 0ull, w1 = 0ull;
; #pragma unroll
;   for (int j = 0; j < NJ; ++j) {
;     const bool e = key[j] == T;
;     const unsigned long long me = __ballot(e);
;     const int before = run + __popcll(me & lm);
;     const bool sel = (key[j] > T) || (e && before < need);
;     run += __popcll(me);
;     const unsigned long long ms = __ballot(sel);
;     if (j < 64) w0 = (lane == j) ? ms : w0; else w1 = (lane == j - 64) ? ms : w1;
;   }
;   if (NJ >= 64 || lane < NJ) *(u32x2*)(mo + 2 * lane) = u32x2{(unsigned)w0, (unsigned)(w0 >> 32)};
;   if (NJ > 64 && lane < NJ - 64) *(u32x2*)(mo + 128 + 2 * lane) = u32x2{(unsigned)w1, (unsigned)(w1 >> 32)};
.LBB0_840:
	s_mov_b32 s98, 0
	v_cmp_le_u32_e64 vcc, s66, v17
	v_cmp_le_u32_e64 s[100:101], s66, v5
	s_bcnt1_i32_b64 s99, vcc
	s_add_i32 s98, s98, s99
	v_writelane_b32 v212, vcc_lo, 0
	v_writelane_b32 v213, vcc_hi, 0
	v_cmp_le_u32_e64 vcc, s66, v2
	s_bcnt1_i32_b64 s99, s[100:101]
	s_add_i32 s98, s98, s99
	v_writelane_b32 v212, s100, 1
	v_writelane_b32 v213, s101, 1
	v_cmp_le_u32_e64 s[100:101], s66, v7
	s_bcnt1_i32_b64 s99, vcc
	s_add_i32 s98, s98, s99
	v_writelane_b32 v212, vcc_lo, 2
	v_writelane_b32 v213, vcc_hi, 2
	v_cmp_le_u32_e64 vcc, s66, v3
	s_bcnt1_i32_b64 s99, s[100:101]
	s_add_i32 s98, s98, s99
	v_writelane_b32 v212, s100, 3
	v_writelane_b32 v213, s101, 3
	v_cmp_le_u32_e64 s[100:101], s66, v9
	s_bcnt1_i32_b64 s99, vcc
	s_add_i32 s98, s98, s99
	v_writelane_b32 v212, vcc_lo, 4
	v_writelane_b32 v213, vcc_hi, 4
	v_cmp_le_u32_e64 vcc, s66, v4
	s_bcnt1_i32_b64 s99, s[100:101]
	s_add_i32 s98, s98, s99
	v_writelane_b32 v212, s100, 5
	v_writelane_b32 v213, s101, 5
	v_cmp_le_u32_e64 s[100:101], s66, v11
	s_bcnt1_i32_b64 s99, vcc
	s_add_i32 s98, s98, s99
	v_writelane_b32 v212, vcc_lo, 6
	v_writelane_b32 v213, vcc_hi, 6
	v_cmp_le_u32_e64 vcc, s66, v6
	s_bcnt1_i32_b64 s99, s[100:101]
	s_add_i32 s98, s98, s99
	v_writelane_b32 v212, s100, 7
	v_writelane_b32 v213, s101, 7
	v_cmp_le_u32_e64 s[100:101], s66, v13
	s_bcnt1_i32_b64 s99, vcc
	s_add_i32 s98, s98, s99
	v_writelane_b32 v212, vcc_lo, 8
	v_writelane_b32 v213, vcc_hi, 8
	v_cmp_le_u32_e64 vcc, s66, v8
	s_bcnt1_i32_b64 s99, s[100:101]
	s_add_i32 s98, s98, s99
	v_writelane_b32 v212, s100, 9
	v_writelane_b32 v213, s101, 9
	v_cmp_le_u32_e64 s[100:101], s66, v14
	s_bcnt1_i32_b64 s99, vcc
	s_add_i32 s98, s98, s99
	v_writelane_b32 v212, vcc_lo, 10
	v_writelane_b32 v213, vcc_hi, 10
	v_cmp_le_u32_e64 vcc, s66, v10
	s_bcnt1_i32_b64 s99, s[100:101]
	s_add_i32 s98, s98, s99
	v_writelane_b32 v212, s100, 11
	v_writelane_b32 v213, s101, 11
	v_cmp_le_u32_e64 s[100:101], s66, v15
	s_bcnt1_i32_b64 s99, vcc
	s_add_i32 s98, s98, s99
	v_writelane_b32 v212, vcc_lo, 12
	v_writelane_b32 v213, vcc_hi, 12
	v_cmp_le_u32_e64 vcc, s66, v12
	s_bcnt1_i32_b64 s99, s[100:101]
	s_add_i32 s98, s98, s99
	v_writelane_b32 v212, s100, 13
	v_writelane_b32 v213, s101, 13
	v_cmp_le_u32_e64 s[100:101], s66, v16
	s_bcnt1_i32_b64 s99, vcc
	s_add_i32 s98, s98, s99
	v_writelane_b32 v212, vcc_lo, 14
	v_writelane_b32 v213, vcc_hi, 14
	s_nop 0
	s_bcnt1_i32_b64 s99, s[100:101]
	s_add_i32 s98, s98, s99
	v_writelane_b32 v212, s100, 15
	v_writelane_b32 v213, s101, 15
	s_cmpk_lg_i32 s98, 0x100
	s_cbranch_scc1 .Lsf_slow_6
	s_mov_b32 s39, s68
	s_mov_b32 s4, s72
	v_cmp_gt_u32_e64 s[100:101], 16, v0
	s_and_saveexec_b64 s[36:37], s[100:101]
	v_lshlrev_b32_e32 v0, 3, v0
	v_readlane_b32 s0, v236, 9
	v_readlane_b32 s1, v236, 10
	s_nop 4
	global_store_dwordx2 v0, v[212:213], s[0:1]
	s_branch .LBB0_842

; template <int NJ>
; DI void b1_select(const float* sc, int nj, unsigned* mo) {
;     ...
;   int cgt = 0;
; #pragma unroll
;   for (int j = 0; j < NJ; ++j) cgt += __popcll(__ballot(key[j] > T));
;   const int need = 256 - cgt;
;   const unsigned long long lm = (1ull << lane) - 1ull;
;   int run = 0;
;   unsigned long long w0 = 0ull, w1 = 0ull;
; #pragma unroll
;   for (int j = 0; j < NJ; ++j) {
;     const bool e = key[j] == T;
;     const unsigned long long me = __ballot(e);
;     const int before = run + __popcll(me & lm);
;     const bool sel = (key[j] > T) || (e && before < need);
;     run += __popcll(me);
;     const unsigned long long ms = __ballot(sel);
;     if (j < 64) w0 = (lane == j) ? ms : w0; else w1 = (lane == j - 64) ? ms : w1;
;   }
;   if (NJ >= 64 || lane < NJ) *(u32x2*)(mo + 2 * lane) = u32x2{(unsigned)w0, (unsigned)(w0 >> 32)};
;   if (NJ > 64 && lane < NJ - 64) *(u32x2*)(mo + 128 + 2 * lane) = u32x2{(unsigned)w1, (unsigned)(w1 >> 32)};
.LBB0_881:
	s_mov_b32 s98, 0
	v_cmp_le_u32_e64 vcc, s36, v17
	v_cmp_le_u32_e64 s[100:101], s36, v3
	s_bcnt1_i32_b64 s99, vcc
	s_add_i32 s98, s98, s99
	v_writelane_b32 v212, vcc_lo, 0
	v_writelane_b32 v213, vcc_hi, 0
	v_cmp_le_u32_e64 vcc, s36, v2
	s_bcnt1_i32_b64 s99, s[100:101]
	s_add_i32 s98, s98, s99
	v_writelane_b32 v212, s100, 1
	v_writelane_b32 v213, s101, 1
	v_cmp_le_u32_e64 s[100:101], s36, v8
	s_bcnt1_i32_b64 s99, vcc
	s_add_i32 s98, s98, s99
	v_writelane_b32 v212, vcc_lo, 2
	v_writelane_b32 v213, vcc_hi, 2
	v_cmp_le_u32_e64 vcc, s36, v4
	s_bcnt1_i32_b64 s99, s[100:101]
	s_add_i32 s98, s98, s99
	v_writelane_b32 v212, s100, 3
	v_writelane_b32 v213, s101, 3
	v_cmp_le_u32_e64 s[100:101], s36, v9
	s_bcnt1_i32_b64 s99, vcc
	s_add_i32 s98, s98, s99
	v_writelane_b32 v212, vcc_lo, 4
	v_writelane_b32 v213, vcc_hi, 4
	v_cmp_le_u32_e64 vcc, s36, v5
	s_bcnt1_i32_b64 s99, s[100:101]
	s_add_i32 s98, s98, s99
	v_writelane_b32 v212, s100, 5
	v_writelane_b32 v213, s101, 5
	v_cmp_le_u32_e64 s[100:101], s36, v11
	s_bcnt1_i32_b64 s99, vcc
	s_add_i32 s98, s98, s99
	v_writelane_b32 v212, vcc_lo, 6
	v_writelane_b32 v213, vcc_hi, 6
	v_cmp_le_u32_e64 vcc, s36, v6
	s_bcnt1_i32_b64 s99, s[100:101]
	s_add_i32 s98, s98, s99
	v_writelane_b32 v212, s100, 7
	v_writelane_b32 v213, s101, 7
	v_cmp_le_u32_e64 s[100:101], s36, v13
	s_bcnt1_i32_b64 s99, vcc
	s_add_i32 s98, s98, s99
	v_writelane_b32 v212, vcc_lo, 8
	v_writelane_b32 v213, vcc_hi, 8
	v_cmp_le_u32_e64 vcc, s36, v7
	s_bcnt1_i32_b64 s99, s[100:101]
	s_add_i32 s98, s98, s99
	v_writelane_b32 v212, s100, 9
	v_writelane_b32 v213, s101, 9
	v_cmp_le_u32_e64 s[100:101], s36, v14
	s_bcnt1_i32_b64 s99, vcc
	s_add_i32 s98, s98, s99
	v_writelane_b32 v212, vcc_lo, 10
	v_writelane_b32 v213, vcc_hi, 10
	v_cmp_le_u32_e64 vcc, s36, v10
	s_bcnt1_i32_b64 s99, s[100:101]
	s_add_i32 s98, s98, s99
	v_writelane_b32 v212, s100, 11
	v_writelane_b32 v213, s101, 11
	v_cmp_le_u32_e64 s[100:101], s36, v15
	s_bcnt1_i32_b64 s99, vcc
	s_add_i32 s98, s98, s99
	v_writelane_b32 v212, vcc_lo, 12
	v_writelane_b32 v213, vcc_hi, 12
	v_cmp_le_u32_e64 vcc, s36, v12
	s_bcnt1_i32_b64 s99, s[100:101]
	s_add_i32 s98, s98, s99
	v_writelane_b32 v212, s100, 13
	v_writelane_b32 v213, s101, 13
	v_cmp_le_u32_e64 s[100:101], s36, v16
	s_bcnt1_i32_b64 s99, vcc
	s_add_i32 s98, s98, s99
	v_writelane_b32 v212, vcc_lo, 14
	v_writelane_b32 v213, vcc_hi, 14
	s_nop 0
	s_bcnt1_i32_b64 s99, s[100:101]
	s_add_i32 s98, s98, s99
	v_writelane_b32 v212, s100, 15
	v_writelane_b32 v213, s101, 15
	s_cmpk_lg_i32 s98, 0x100
	s_cbranch_scc1 .Lsf_slow_7
	v_cmp_gt_u32_e64 s[100:101], 16, v0
	s_and_saveexec_b64 s[34:35], s[100:101]
	v_lshlrev_b32_e32 v0, 3, v0
	v_readlane_b32 s0, v236, 9
	v_readlane_b32 s1, v236, 10
	s_nop 4
	global_store_dwordx2 v0, v[212:213], s[0:1] offset:256
	s_branch .LBB0_883

; template <int NJ>
; DI void b1_select(const float* sc, int nj, unsigned* mo) {
;     ...
;   int cgt = 0;
; #pragma unroll
;   for (int j = 0; j < NJ; ++j) cgt += __popcll(__ballot(key[j] > T));
;   const int need = 256 - cgt;
;   const unsigned long long lm = (1ull << lane) - 1ull;
;   int run = 0;
;   unsigned long long w0 = 0ull, w1 = 0ull;
; #pragma unroll
;   for (int j = 0; j < NJ; ++j) {
;     const bool e = key[j] == T;
;     const unsigned long long me = __ballot(e);
;     const int before = run + __popcll(me & lm);
;     const bool sel = (key[j] > T) || (e && before < need);
;     run += __popcll(me);
;     const unsigned long long ms = __ballot(sel);
;     if (j < 64) w0 = (lane == j) ? ms : w0; else w1 = (lane == j - 64) ? ms : w1;
;   }
;   if (NJ >= 64 || lane < NJ) *(u32x2*)(mo + 2 * lane) = u32x2{(unsigned)w0, (unsigned)(w0 >> 32)};
;   if (NJ > 64 && lane < NJ - 64) *(u32x2*)(mo + 128 + 2 * lane) = u32x2{(unsigned)w1, (unsigned)(w1 >> 32)};
.LBB0_916:
	s_mov_b32 s98, 0
	v_cmp_le_u32_e64 vcc, s50, v13
	v_cmp_le_u32_e64 s[100:101], s50, v5
	s_bcnt1_i32_b64 s99, vcc
	s_add_i32 s98, s98, s99
	v_writelane_b32 v212, vcc_lo, 0
	v_writelane_b32 v213, vcc_hi, 0
	v_cmp_le_u32_e64 vcc, s50, v2
	s_bcnt1_i32_b64 s99, s[100:101]
	s_add_i32 s98, s98, s99
	v_writelane_b32 v212, s100, 1
	v_writelane_b32 v213, s101, 1
	v_cmp_le_u32_e64 s[100:101], s50, v7
	s_bcnt1_i32_b64 s99, vcc
	s_add_i32 s98, s98, s99
	v_writelane_b32 v212, vcc_lo, 2
	v_writelane_b32 v213, vcc_hi, 2
	v_cmp_le_u32_e64 vcc, s50, v3
	s_bcnt1_i32_b64 s99, s[100:101]
	s_add_i32 s98, s98, s99
	v_writelane_b32 v212, s100, 3
	v_writelane_b32 v213, s101, 3
	v_cmp_le_u32_e64 s[100:101], s50, v9
	s_bcnt1_i32_b64 s99, vcc
	s_add_i32 s98, s98, s99
	v_writelane_b32 v212, vcc_lo, 4
	v_writelane_b32 v213, vcc_hi, 4
	v_cmp_le_u32_e64 vcc, s50, v4
	s_bcnt1_i32_b64 s99, s[100:101]
	s_add_i32 s98, s98, s99
	v_writelane_b32 v212, s100, 5
	v_writelane_b32 v213, s101, 5
	v_cmp_le_u32_e64 s[100:101], s50, v10
	s_bcnt1_i32_b64 s99, vcc
	s_add_i32 s98, s98, s99
	v_writelane_b32 v212, vcc_lo, 6
	v_writelane_b32 v213, vcc_hi, 6
	v_cmp_le_u32_e64 vcc, s50, v6
	s_bcnt1_i32_b64 s99, s[100:101]
	s_add_i32 s98, s98, s99
	v_writelane_b32 v212, s100, 7
	v_writelane_b32 v213, s101, 7
	v_cmp_le_u32_e64 s[100:101], s50, v11
	s_bcnt1_i32_b64 s99, vcc
	s_add_i32 s98, s98, s99
	v_writelane_b32 v212, vcc_lo, 8
	v_writelane_b32 v213, vcc_hi, 8
	v_cmp_le_u32_e64 vcc, s50, v8
	s_bcnt1_i32_b64 s99, s[100:101]
	s_add_i32 s98, s98, s99
	v_writelane_b32 v212, s100, 9
	v_writelane_b32 v213, s101, 9
	v_cmp_le_u32_e64 s[100:101], s50, v12
	s_bcnt1_i32_b64 s99, vcc
	s_add_i32 s98, s98, s99
	v_writelane_b32 v212, vcc_lo, 10
	v_writelane_b32 v213, vcc_hi, 10
	s_nop 0
	s_bcnt1_i32_b64 s99, s[100:101]
	s_add_i32 s98, s98, s99
	v_writelane_b32 v212, s100, 11
	v_writelane_b32 v213, s101, 11
	s_cmpk_lg_i32 s98, 0x100
	s_cbranch_scc1 .Lsf_slow_8
	v_cmp_gt_u32_e64 s[100:101], 12, v0
	s_and_saveexec_b64 s[26:27], s[100:101]
	v_lshlrev_b32_e32 v0, 3, v0
	v_readlane_b32 s0, v236, 9
	v_readlane_b32 s1, v236, 10
	s_nop 4
	global_store_dwordx2 v0, v[212:213], s[0:1]
	s_branch .LBB0_918

; template <int NJ>
; DI void b1_select(const float* sc, int nj, unsigned* mo) {
;     ...
;   int cgt = 0;
; #pragma unroll
;   for (int j = 0; j < NJ; ++j) cgt += __popcll(__ballot(key[j] > T));
;   const int need = 256 - cgt;
;   const unsigned long long lm = (1ull << lane) - 1ull;
;   int run = 0;
;   unsigned long long w0 = 0ull, w1 = 0ull;
; #pragma unroll
;   for (int j = 0; j < NJ; ++j) {
;     const bool e = key[j] == T;
;     const unsigned long long me = __ballot(e);
;     const int before = run + __popcll(me & lm);
;     const bool sel = (key[j] > T) || (e && before < need);
;     run += __popcll(me);
;     const unsigned long long ms = __ballot(sel);
;     if (j < 64) w0 = (lane == j) ? ms : w0; else w1 = (lane == j - 64) ? ms : w1;
;   }
;   if (NJ >= 64 || lane < NJ) *(u32x2*)(mo + 2 * lane) = u32x2{(unsigned)w0, (unsigned)(w0 >> 32)};
;   if (NJ > 64 && lane < NJ - 64) *(u32x2*)(mo + 128 + 2 * lane) = u32x2{(unsigned)w1, (unsigned)(w1 >> 32)};
.LBB0_949:
	s_mov_b32 s98, 0
	v_cmp_le_u32_e64 vcc, s26, v13
	v_cmp_le_u32_e64 s[100:101], s26, v5
	s_bcnt1_i32_b64 s99, vcc
	s_add_i32 s98, s98, s99
	v_writelane_b32 v212, vcc_lo, 0
	v_writelane_b32 v213, vcc_hi, 0
	v_cmp_le_u32_e64 vcc, s26, v2
	s_bcnt1_i32_b64 s99, s[100:101]
	s_add_i32 s98, s98, s99
	v_writelane_b32 v212, s100, 1
	v_writelane_b32 v213, s101, 1
	v_cmp_le_u32_e64 s[100:101], s26, v7
	s_bcnt1_i32_b64 s99, vcc
	s_add_i32 s98, s98, s99
	v_writelane_b32 v212, vcc_lo, 2
	v_writelane_b32 v213, vcc_hi, 2
	v_cmp_le_u32_e64 vcc, s26, v3
	s_bcnt1_i32_b64 s99, s[100:101]
	s_add_i32 s98, s98, s99
	v_writelane_b32 v212, s100, 3
	v_writelane_b32 v213, s101, 3
	v_cmp_le_u32_e64 s[100:101], s26, v9
	s_bcnt1_i32_b64 s99, vcc
	s_add_i32 s98, s98, s99
	v_writelane_b32 v212, vcc_lo, 4
	v_writelane_b32 v213, vcc_hi, 4
	v_cmp_le_u32_e64 vcc, s26, v4
	s_bcnt1_i32_b64 s99, s[100:101]
	s_add_i32 s98, s98, s99
	v_writelane_b32 v212, s100, 5
	v_writelane_b32 v213, s101, 5
	v_cmp_le_u32_e64 s[100:101], s26, v10
	s_bcnt1_i32_b64 s99, vcc
	s_add_i32 s98, s98, s99
	v_writelane_b32 v212, vcc_lo, 6
	v_writelane_b32 v213, vcc_hi, 6
	v_cmp_le_u32_e64 vcc, s26, v6
	s_bcnt1_i32_b64 s99, s[100:101]
	s_add_i32 s98, s98, s99
	v_writelane_b32 v212, s100, 7
	v_writelane_b32 v213, s101, 7
	v_cmp_le_u32_e64 s[100:101], s26, v11
	s_bcnt1_i32_b64 s99, vcc
	s_add_i32 s98, s98, s99
	v_writelane_b32 v212, vcc_lo, 8
	v_writelane_b32 v213, vcc_hi, 8
	v_cmp_le_u32_e64 vcc, s26, v8
	s_bcnt1_i32_b64 s99, s[100:101]
	s_add_i32 s98, s98, s99
	v_writelane_b32 v212, s100, 9
	v_writelane_b32 v213, s101, 9
	v_cmp_le_u32_e64 s[100:101], s26, v12
	s_bcnt1_i32_b64 s99, vcc
	s_add_i32 s98, s98, s99
	v_writelane_b32 v212, vcc_lo, 10
	v_writelane_b32 v213, vcc_hi, 10
	s_nop 0
	s_bcnt1_i32_b64 s99, s[100:101]
	s_add_i32 s98, s98, s99
	v_writelane_b32 v212, s100, 11
	v_writelane_b32 v213, s101, 11
	s_cmpk_lg_i32 s98, 0x100
	s_cbranch_scc1 .Lsf_slow_9
	v_cmp_gt_u32_e64 s[100:101], 12, v0
	s_and_saveexec_b64 s[24:25], s[100:101]
	v_lshlrev_b32_e32 v0, 3, v0
	v_readlane_b32 s0, v236, 9
	v_readlane_b32 s1, v236, 10
	s_nop 4
	global_store_dwordx2 v0, v[212:213], s[0:1] offset:256
	s_branch .LBB0_951

; template <int NJ>
; DI void b1_select(const float* sc, int nj, unsigned* mo) {
;     ...
;   int cgt = 0;
; #pragma unroll
;   for (int j = 0; j < NJ; ++j) cgt += __popcll(__ballot(key[j] > T));
;   const int need = 256 - cgt;
;   const unsigned long long lm = (1ull << lane) - 1ull;
;   int run = 0;
;   unsigned long long w0 = 0ull, w1 = 0ull;
; #pragma unroll
;   for (int j = 0; j < NJ; ++j) {
;     const bool e = key[j] == T;
;     const unsigned long long me = __ballot(e);
;     const int before = run + __popcll(me & lm);
;     const bool sel = (key[j] > T) || (e && before < need);
;     run += __popcll(me);
;     const unsigned long long ms = __ballot(sel);
;     if (j < 64) w0 = (lane == j) ? ms : w0; else w1 = (lane == j - 64) ? ms : w1;
;   }
;   if (NJ >= 64 || lane < NJ) *(u32x2*)(mo + 2 * lane) = u32x2{(unsigned)w0, (unsigned)(w0 >> 32)};
;   if (NJ > 64 && lane < NJ - 64) *(u32x2*)(mo + 128 + 2 * lane) = u32x2{(unsigned)w1, (unsigned)(w1 >> 32)};
.LBB0_1027:
	s_mov_b32 s98, 0
	v_cmp_le_u32_e64 vcc, s97, v33
	v_cmp_le_u32_e64 s[100:101], s97, v5
	s_bcnt1_i32_b64 s99, vcc
	s_add_i32 s98, s98, s99
	v_writelane_b32 v212, vcc_lo, 0
	v_writelane_b32 v213, vcc_hi, 0
	v_cmp_le_u32_e64 vcc, s97, v2
	s_bcnt1_i32_b64 s99, s[100:101]
	s_add_i32 s98, s98, s99
	v_writelane_b32 v212, s100, 1
	v_writelane_b32 v213, s101, 1
	v_cmp_le_u32_e64 s[100:101], s97, v7
	s_bcnt1_i32_b64 s99, vcc
	s_add_i32 s98, s98, s99
	v_writelane_b32 v212, vcc_lo, 2
	v_writelane_b32 v213, vcc_hi, 2
	v_cmp_le_u32_e64 vcc, s97, v3
	s_bcnt1_i32_b64 s99, s[100:101]
	s_add_i32 s98, s98, s99
	v_writelane_b32 v212, s100, 3
	v_writelane_b32 v213, s101, 3
	v_cmp_le_u32_e64 s[100:101], s97, v9
	s_bcnt1_i32_b64 s99, vcc
	s_add_i32 s98, s98, s99
	v_writelane_b32 v212, vcc_lo, 4
	v_writelane_b32 v213, vcc_hi, 4
	v_cmp_le_u32_e64 vcc, s97, v4
	s_bcnt1_i32_b64 s99, s[100:101]
	s_add_i32 s98, s98, s99
	v_writelane_b32 v212, s100, 5
	v_writelane_b32 v213, s101, 5
	v_cmp_le_u32_e64 s[100:101], s97, v11
	s_bcnt1_i32_b64 s99, vcc
	s_add_i32 s98, s98, s99
	v_writelane_b32 v212, vcc_lo, 6
	v_writelane_b32 v213, vcc_hi, 6
	v_cmp_le_u32_e64 vcc, s97, v6
	s_bcnt1_i32_b64 s99, s[100:101]
	s_add_i32 s98, s98, s99
	v_writelane_b32 v212, s100, 7
	v_writelane_b32 v213, s101, 7
	v_cmp_le_u32_e64 s[100:101], s97, v13
	s_bcnt1_i32_b64 s99, vcc
	s_add_i32 s98, s98, s99
	v_writelane_b32 v212, vcc_lo, 8
	v_writelane_b32 v213, vcc_hi, 8
	v_cmp_le_u32_e64 vcc, s97, v8
	s_bcnt1_i32_b64 s99, s[100:101]
	s_add_i32 s98, s98, s99
	v_writelane_b32 v212, s100, 9
	v_writelane_b32 v213, s101, 9
	v_cmp_le_u32_e64 s[100:101], s97, v15
	s_bcnt1_i32_b64 s99, vcc
	s_add_i32 s98, s98, s99
	v_writelane_b32 v212, vcc_lo, 10
	v_writelane_b32 v213, vcc_hi, 10
	v_cmp_le_u32_e64 vcc, s97, v10
	s_bcnt1_i32_b64 s99, s[100:101]
	s_add_i32 s98, s98, s99
	v_writelane_b32 v212, s100, 11
	v_writelane_b32 v213, s101, 11
	v_cmp_le_u32_e64 s[100:101], s97, v17
	s_bcnt1_i32_b64 s99, vcc
	s_add_i32 s98, s98, s99
	v_writelane_b32 v212, vcc_lo, 12
	v_writelane_b32 v213, vcc_hi, 12
	v_cmp_le_u32_e64 vcc, s97, v12
	s_bcnt1_i32_b64 s99, s[100:101]
	s_add_i32 s98, s98, s99
	v_writelane_b32 v212, s100, 13
	v_writelane_b32 v213, s101, 13
	v_cmp_le_u32_e64 s[100:101], s97, v19
	s_bcnt1_i32_b64 s99, vcc
	s_add_i32 s98, s98, s99
	v_writelane_b32 v212, vcc_lo, 14
	v_writelane_b32 v213, vcc_hi, 14
	v_cmp_le_u32_e64 vcc, s97, v14
	s_bcnt1_i32_b64 s99, s[100:101]
	s_add_i32 s98, s98, s99
	v_writelane_b32 v212, s100, 15
	v_writelane_b32 v213, s101, 15
	v_cmp_le_u32_e64 s[100:101], s97, v21
	s_bcnt1_i32_b64 s99, vcc
	s_add_i32 s98, s98, s99
	v_writelane_b32 v212, vcc_lo, 16
	v_writelane_b32 v213, vcc_hi, 16
	v_cmp_le_u32_e64 vcc, s97, v16
	s_bcnt1_i32_b64 s99, s[100:101]
	s_add_i32 s98, s98, s99
	v_writelane_b32 v212, s100, 17
	v_writelane_b32 v213, s101, 17
	v_cmp_le_u32_e64 s[100:101], s97, v23
	s_bcnt1_i32_b64 s99, vcc
	s_add_i32 s98, s98, s99
	v_writelane_b32 v212, vcc_lo, 18
	v_writelane_b32 v213, vcc_hi, 18
	v_cmp_le_u32_e64 vcc, s97, v18
	s_bcnt1_i32_b64 s99, s[100:101]
	s_add_i32 s98, s98, s99
	v_writelane_b32 v212, s100, 19
	v_writelane_b32 v213, s101, 19
	v_cmp_le_u32_e64 s[100:101], s97, v26
	s_bcnt1_i32_b64 s99, vcc
	s_add_i32 s98, s98, s99
	v_writelane_b32 v212, vcc_lo, 20
	v_writelane_b32 v213, vcc_hi, 20
	v_cmp_le_u32_e64 vcc, s97, v20
	s_bcnt1_i32_b64 s99, s[100:101]
	s_add_i32 s98, s98, s99
	v_writelane_b32 v212, s100, 21
	v_writelane_b32 v213, s101, 21
	v_cmp_le_u32_e64 s[100:101], s97, v28
	s_bcnt1_i32_b64 s99, vcc
	s_add_i32 s98, s98, s99
	v_writelane_b32 v212, vcc_lo, 22
	v_writelane_b32 v213, vcc_hi, 22
	v_cmp_le_u32_e64 vcc, s97, v22
	s_bcnt1_i32_b64 s99, s[100:101]
	s_add_i32 s98, s98, s99
	v_writelane_b32 v212, s100, 23
	v_writelane_b32 v213, s101, 23
	v_cmp_le_u32_e64 s[100:101], s97, v29
	s_bcnt1_i32_b64 s99, vcc
	s_add_i32 s98, s98, s99
	v_writelane_b32 v212, vcc_lo, 24
	v_writelane_b32 v213, vcc_hi, 24
	v_cmp_le_u32_e64 vcc, s97, v24
	s_bcnt1_i32_b64 s99, s[100:101]
	s_add_i32 s98, s98, s99
	v_writelane_b32 v212, s100, 25
	v_writelane_b32 v213, s101, 25
	v_cmp_le_u32_e64 s[100:101], s97, v30
	s_bcnt1_i32_b64 s99, vcc
	s_add_i32 s98, s98, s99
	v_writelane_b32 v212, vcc_lo, 26
	v_writelane_b32 v213, vcc_hi, 26
	v_cmp_le_u32_e64 vcc, s97, v25
	s_bcnt1_i32_b64 s99, s[100:101]
	s_add_i32 s98, s98, s99
	v_writelane_b32 v212, s100, 27
	v_writelane_b32 v213, s101, 27
	v_cmp_le_u32_e64 s[100:101], s97, v31
	s_bcnt1_i32_b64 s99, vcc
	s_add_i32 s98, s98, s99
	v_writelane_b32 v212, vcc_lo, 28
	v_writelane_b32 v213, vcc_hi, 28
	v_cmp_le_u32_e64 vcc, s97, v27
	s_bcnt1_i32_b64 s99, s[100:101]
	s_add_i32 s98, s98, s99
	v_writelane_b32 v212, s100, 29
	v_writelane_b32 v213, s101, 29
	v_cmp_le_u32_e64 s[100:101], s97, v32
	s_bcnt1_i32_b64 s99, vcc
	s_add_i32 s98, s98, s99
	v_writelane_b32 v212, vcc_lo, 30
	v_writelane_b32 v213, vcc_hi, 30
	s_nop 0
	s_bcnt1_i32_b64 s99, s[100:101]
	s_add_i32 s98, s98, s99
	v_writelane_b32 v212, s100, 31
	v_writelane_b32 v213, s101, 31
	s_cmpk_lg_i32 s98, 0x100
	s_cbranch_scc1 .Lsf_slow_10
	v_writelane_b32 v237, s40, 19
	v_writelane_b32 v237, s41, 20
	v_cmp_gt_u32_e64 s[100:101], 32, v0
	s_and_saveexec_b64 s[68:69], s[100:101]
	v_lshlrev_b32_e32 v0, 3, v0
	v_readlane_b32 s0, v236, 9
	v_readlane_b32 s1, v236, 10
	s_nop 4
	global_store_dwordx2 v0, v[212:213], s[0:1]
	s_branch .LBB0_1029

; template <int NJ>
; DI void b1_select(const float* sc, int nj, unsigned* mo) {
;     ...
;   int cgt = 0;
; #pragma unroll
;   for (int j = 0; j < NJ; ++j) cgt += __popcll(__ballot(key[j] > T));
;   const int need = 256 - cgt;
;   const unsigned long long lm = (1ull << lane) - 1ull;
;   int run = 0;
;   unsigned long long w0 = 0ull, w1 = 0ull;
; #pragma unroll
;   for (int j = 0; j < NJ; ++j) {
;     const bool e = key[j] == T;
;     const unsigned long long me = __ballot(e);
;     const int before = run + __popcll(me & lm);
;     const bool sel = (key[j] > T) || (e && before < need);
;     run += __popcll(me);
;     const unsigned long long ms = __ballot(sel);
;     if (j < 64) w0 = (lane == j) ? ms : w0; else w1 = (lane == j - 64) ? ms : w1;
;   }
;   if (NJ >= 64 || lane < NJ) *(u32x2*)(mo + 2 * lane) = u32x2{(unsigned)w0, (unsigned)(w0 >> 32)};
;   if (NJ > 64 && lane < NJ - 64) *(u32x2*)(mo + 128 + 2 * lane) = u32x2{(unsigned)w1, (unsigned)(w1 >> 32)};
.LBB0_1100:
	s_mov_b32 s98, 0
	v_cmp_le_u32_e64 vcc, s72, v33
	v_cmp_le_u32_e64 s[100:101], s72, v5
	s_bcnt1_i32_b64 s99, vcc
	s_add_i32 s98, s98, s99
	v_writelane_b32 v212, vcc_lo, 0
	v_writelane_b32 v213, vcc_hi, 0
	v_cmp_le_u32_e64 vcc, s72, v2
	s_bcnt1_i32_b64 s99, s[100:101]
	s_add_i32 s98, s98, s99
	v_writelane_b32 v212, s100, 1
	v_writelane_b32 v213, s101, 1
	v_cmp_le_u32_e64 s[100:101], s72, v7
	s_bcnt1_i32_b64 s99, vcc
	s_add_i32 s98, s98, s99
	v_writelane_b32 v212, vcc_lo, 2
	v_writelane_b32 v213, vcc_hi, 2
	v_cmp_le_u32_e64 vcc, s72, v3
	s_bcnt1_i32_b64 s99, s[100:101]
	s_add_i32 s98, s98, s99
	v_writelane_b32 v212, s100, 3
	v_writelane_b32 v213, s101, 3
	v_cmp_le_u32_e64 s[100:101], s72, v9
	s_bcnt1_i32_b64 s99, vcc
	s_add_i32 s98, s98, s99
	v_writelane_b32 v212, vcc_lo, 4
	v_writelane_b32 v213, vcc_hi, 4
	v_cmp_le_u32_e64 vcc, s72, v4
	s_bcnt1_i32_b64 s99, s[100:101]
	s_add_i32 s98, s98, s99
	v_writelane_b32 v212, s100, 5
	v_writelane_b32 v213, s101, 5
	v_cmp_le_u32_e64 s[100:101], s72, v11
	s_bcnt1_i32_b64 s99, vcc
	s_add_i32 s98, s98, s99
	v_writelane_b32 v212, vcc_lo, 6
	v_writelane_b32 v213, vcc_hi, 6
	v_cmp_le_u32_e64 vcc, s72, v6
	s_bcnt1_i32_b64 s99, s[100:101]
	s_add_i32 s98, s98, s99
	v_writelane_b32 v212, s100, 7
	v_writelane_b32 v213, s101, 7
	v_cmp_le_u32_e64 s[100:101], s72, v13
	s_bcnt1_i32_b64 s99, vcc
	s_add_i32 s98, s98, s99
	v_writelane_b32 v212, vcc_lo, 8
	v_writelane_b32 v213, vcc_hi, 8
	v_cmp_le_u32_e64 vcc, s72, v8
	s_bcnt1_i32_b64 s99, s[100:101]
	s_add_i32 s98, s98, s99
	v_writelane_b32 v212, s100, 9
	v_writelane_b32 v213, s101, 9
	v_cmp_le_u32_e64 s[100:101], s72, v15
	s_bcnt1_i32_b64 s99, vcc
	s_add_i32 s98, s98, s99
	v_writelane_b32 v212, vcc_lo, 10
	v_writelane_b32 v213, vcc_hi, 10
	v_cmp_le_u32_e64 vcc, s72, v10
	s_bcnt1_i32_b64 s99, s[100:101]
	s_add_i32 s98, s98, s99
	v_writelane_b32 v212, s100, 11
	v_writelane_b32 v213, s101, 11
	v_cmp_le_u32_e64 s[100:101], s72, v17
	s_bcnt1_i32_b64 s99, vcc
	s_add_i32 s98, s98, s99
	v_writelane_b32 v212, vcc_lo, 12
	v_writelane_b32 v213, vcc_hi, 12
	v_cmp_le_u32_e64 vcc, s72, v12
	s_bcnt1_i32_b64 s99, s[100:101]
	s_add_i32 s98, s98, s99
	v_writelane_b32 v212, s100, 13
	v_writelane_b32 v213, s101, 13
	v_cmp_le_u32_e64 s[100:101], s72, v19
	s_bcnt1_i32_b64 s99, vcc
	s_add_i32 s98, s98, s99
	v_writelane_b32 v212, vcc_lo, 14
	v_writelane_b32 v213, vcc_hi, 14
	v_cmp_le_u32_e64 vcc, s72, v14
	s_bcnt1_i32_b64 s99, s[100:101]
	s_add_i32 s98, s98, s99
	v_writelane_b32 v212, s100, 15
	v_writelane_b32 v213, s101, 15
	v_cmp_le_u32_e64 s[100:101], s72, v21
	s_bcnt1_i32_b64 s99, vcc
	s_add_i32 s98, s98, s99
	v_writelane_b32 v212, vcc_lo, 16
	v_writelane_b32 v213, vcc_hi, 16
	v_cmp_le_u32_e64 vcc, s72, v16
	s_bcnt1_i32_b64 s99, s[100:101]
	s_add_i32 s98, s98, s99
	v_writelane_b32 v212, s100, 17
	v_writelane_b32 v213, s101, 17
	v_cmp_le_u32_e64 s[100:101], s72, v23
	s_bcnt1_i32_b64 s99, vcc
	s_add_i32 s98, s98, s99
	v_writelane_b32 v212, vcc_lo, 18
	v_writelane_b32 v213, vcc_hi, 18
	v_cmp_le_u32_e64 vcc, s72, v18
	s_bcnt1_i32_b64 s99, s[100:101]
	s_add_i32 s98, s98, s99
	v_writelane_b32 v212, s100, 19
	v_writelane_b32 v213, s101, 19
	v_cmp_le_u32_e64 s[100:101], s72, v26
	s_bcnt1_i32_b64 s99, vcc
	s_add_i32 s98, s98, s99
	v_writelane_b32 v212, vcc_lo, 20
	v_writelane_b32 v213, vcc_hi, 20
	v_cmp_le_u32_e64 vcc, s72, v20
	s_bcnt1_i32_b64 s99, s[100:101]
	s_add_i32 s98, s98, s99
	v_writelane_b32 v212, s100, 21
	v_writelane_b32 v213, s101, 21
	v_cmp_le_u32_e64 s[100:101], s72, v28
	s_bcnt1_i32_b64 s99, vcc
	s_add_i32 s98, s98, s99
	v_writelane_b32 v212, vcc_lo, 22
	v_writelane_b32 v213, vcc_hi, 22
	v_cmp_le_u32_e64 vcc, s72, v22
	s_bcnt1_i32_b64 s99, s[100:101]
	s_add_i32 s98, s98, s99
	v_writelane_b32 v212, s100, 23
	v_writelane_b32 v213, s101, 23
	v_cmp_le_u32_e64 s[100:101], s72, v29
	s_bcnt1_i32_b64 s99, vcc
	s_add_i32 s98, s98, s99
	v_writelane_b32 v212, vcc_lo, 24
	v_writelane_b32 v213, vcc_hi, 24
	v_cmp_le_u32_e64 vcc, s72, v24
	s_bcnt1_i32_b64 s99, s[100:101]
	s_add_i32 s98, s98, s99
	v_writelane_b32 v212, s100, 25
	v_writelane_b32 v213, s101, 25
	v_cmp_le_u32_e64 s[100:101], s72, v30
	s_bcnt1_i32_b64 s99, vcc
	s_add_i32 s98, s98, s99
	v_writelane_b32 v212, vcc_lo, 26
	v_writelane_b32 v213, vcc_hi, 26
	v_cmp_le_u32_e64 vcc, s72, v25
	s_bcnt1_i32_b64 s99, s[100:101]
	s_add_i32 s98, s98, s99
	v_writelane_b32 v212, s100, 27
	v_writelane_b32 v213, s101, 27
	v_cmp_le_u32_e64 s[100:101], s72, v32
	s_bcnt1_i32_b64 s99, vcc
	s_add_i32 s98, s98, s99
	v_writelane_b32 v212, vcc_lo, 28
	v_writelane_b32 v213, vcc_hi, 28
	v_cmp_le_u32_e64 vcc, s72, v27
	s_bcnt1_i32_b64 s99, s[100:101]
	s_add_i32 s98, s98, s99
	v_writelane_b32 v212, s100, 29
	v_writelane_b32 v213, s101, 29
	v_cmp_le_u32_e64 s[100:101], s72, v31
	s_bcnt1_i32_b64 s99, vcc
	s_add_i32 s98, s98, s99
	v_writelane_b32 v212, vcc_lo, 30
	v_writelane_b32 v213, vcc_hi, 30
	s_nop 0
	s_bcnt1_i32_b64 s99, s[100:101]
	s_add_i32 s98, s98, s99
	v_writelane_b32 v212, s100, 31
	v_writelane_b32 v213, s101, 31
	s_cmpk_lg_i32 s98, 0x100
	s_cbranch_scc1 .Lsf_slow_11
	v_cmp_gt_u32_e64 s[100:101], 32, v0
	s_and_saveexec_b64 s[68:69], s[100:101]
	v_lshlrev_b32_e32 v0, 3, v0
	v_readlane_b32 s0, v236, 9
	v_readlane_b32 s1, v236, 10
	s_nop 4
	global_store_dwordx2 v0, v[212:213], s[0:1] offset:256
	s_branch .LBB0_1102

; template <int NJ>
; DI void b1_select(const float* sc, int nj, unsigned* mo) {
;     ...
;   int cgt = 0;
; #pragma unroll
;   for (int j = 0; j < NJ; ++j) cgt += __popcll(__ballot(key[j] > T));
;   const int need = 256 - cgt;
;   const unsigned long long lm = (1ull << lane) - 1ull;
;   int run = 0;
;   unsigned long long w0 = 0ull, w1 = 0ull;
; #pragma unroll
;   for (int j = 0; j < NJ; ++j) {
;     const bool e = key[j] == T;
;     const unsigned long long me = __ballot(e);
;     const int before = run + __popcll(me & lm);
;     const bool sel = (key[j] > T) || (e && before < need);
;     run += __popcll(me);
;     const unsigned long long ms = __ballot(sel);
;     if (j < 64) w0 = (lane == j) ? ms : w0; else w1 = (lane == j - 64) ? ms : w1;
;   }
;   if (NJ >= 64 || lane < NJ) *(u32x2*)(mo + 2 * lane) = u32x2{(unsigned)w0, (unsigned)(w0 >> 32)};
;   if (NJ > 64 && lane < NJ - 64) *(u32x2*)(mo + 128 + 2 * lane) = u32x2{(unsigned)w1, (unsigned)(w1 >> 32)};
.LBB0_1127:
	s_mov_b32 s98, 0
	v_cmp_le_u32_e64 vcc, s30, v9
	v_cmp_le_u32_e64 s[100:101], s30, v5
	s_bcnt1_i32_b64 s99, vcc
	s_add_i32 s98, s98, s99
	v_writelane_b32 v212, vcc_lo, 0
	v_writelane_b32 v213, vcc_hi, 0
	v_cmp_le_u32_e64 vcc, s30, v2
	s_bcnt1_i32_b64 s99, s[100:101]
	s_add_i32 s98, s98, s99
	v_writelane_b32 v212, s100, 1
	v_writelane_b32 v213, s101, 1
	v_cmp_le_u32_e64 s[100:101], s30, v6
	s_bcnt1_i32_b64 s99, vcc
	s_add_i32 s98, s98, s99
	v_writelane_b32 v212, vcc_lo, 2
	v_writelane_b32 v213, vcc_hi, 2
	v_cmp_le_u32_e64 vcc, s30, v3
	s_bcnt1_i32_b64 s99, s[100:101]
	s_add_i32 s98, s98, s99
	v_writelane_b32 v212, s100, 3
	v_writelane_b32 v213, s101, 3
	v_cmp_le_u32_e64 s[100:101], s30, v7
	s_bcnt1_i32_b64 s99, vcc
	s_add_i32 s98, s98, s99
	v_writelane_b32 v212, vcc_lo, 4
	v_writelane_b32 v213, vcc_hi, 4
	v_cmp_le_u32_e64 vcc, s30, v4
	s_bcnt1_i32_b64 s99, s[100:101]
	s_add_i32 s98, s98, s99
	v_writelane_b32 v212, s100, 5
	v_writelane_b32 v213, s101, 5
	v_cmp_le_u32_e64 s[100:101], s30, v8
	s_bcnt1_i32_b64 s99, vcc
	s_add_i32 s98, s98, s99
	v_writelane_b32 v212, vcc_lo, 6
	v_writelane_b32 v213, vcc_hi, 6
	s_nop 0
	s_bcnt1_i32_b64 s99, s[100:101]
	s_add_i32 s98, s98, s99
	v_writelane_b32 v212, s100, 7
	v_writelane_b32 v213, s101, 7
	s_cmpk_lg_i32 s98, 0x100
	s_cbranch_scc1 .Lsf_slow_12
	v_cmp_gt_u32_e64 s[100:101], 8, v0
	s_and_saveexec_b64 s[16:17], s[100:101]
	v_lshlrev_b32_e32 v0, 3, v0
	v_readlane_b32 s0, v236, 9
	v_readlane_b32 s1, v236, 10
	s_nop 4
	global_store_dwordx2 v0, v[212:213], s[0:1]
	s_branch .LBB0_1129

; template <int NJ>
; DI void b1_select(const float* sc, int nj, unsigned* mo) {
;     ...
;   int cgt = 0;
; #pragma unroll
;   for (int j = 0; j < NJ; ++j) cgt += __popcll(__ballot(key[j] > T));
;   const int need = 256 - cgt;
;   const unsigned long long lm = (1ull << lane) - 1ull;
;   int run = 0;
;   unsigned long long w0 = 0ull, w1 = 0ull;
; #pragma unroll
;   for (int j = 0; j < NJ; ++j) {
;     const bool e = key[j] == T;
;     const unsigned long long me = __ballot(e);
;     const int before = run + __popcll(me & lm);
;     const bool sel = (key[j] > T) || (e && before < need);
;     run += __popcll(me);
;     const unsigned long long ms = __ballot(sel);
;     if (j < 64) w0 = (lane == j) ? ms : w0; else w1 = (lane == j - 64) ? ms : w1;
;   }
;   if (NJ >= 64 || lane < NJ) *(u32x2*)(mo + 2 * lane) = u32x2{(unsigned)w0, (unsigned)(w0 >> 32)};
;   if (NJ > 64 && lane < NJ - 64) *(u32x2*)(mo + 128 + 2 * lane) = u32x2{(unsigned)w1, (unsigned)(w1 >> 32)};
.LBB0_1152:
	s_mov_b32 s98, 0
	v_cmp_le_u32_e64 vcc, s18, v9
	v_cmp_le_u32_e64 s[100:101], s18, v5
	s_bcnt1_i32_b64 s99, vcc
	s_add_i32 s98, s98, s99
	v_writelane_b32 v212, vcc_lo, 0
	v_writelane_b32 v213, vcc_hi, 0
	v_cmp_le_u32_e64 vcc, s18, v2
	s_bcnt1_i32_b64 s99, s[100:101]
	s_add_i32 s98, s98, s99
	v_writelane_b32 v212, s100, 1
	v_writelane_b32 v213, s101, 1
	v_cmp_le_u32_e64 s[100:101], s18, v6
	s_bcnt1_i32_b64 s99, vcc
	s_add_i32 s98, s98, s99
	v_writelane_b32 v212, vcc_lo, 2
	v_writelane_b32 v213, vcc_hi, 2
	v_cmp_le_u32_e64 vcc, s18, v3
	s_bcnt1_i32_b64 s99, s[100:101]
	s_add_i32 s98, s98, s99
	v_writelane_b32 v212, s100, 3
	v_writelane_b32 v213, s101, 3
	v_cmp_le_u32_e64 s[100:101], s18, v7
	s_bcnt1_i32_b64 s99, vcc
	s_add_i32 s98, s98, s99
	v_writelane_b32 v212, vcc_lo, 4
	v_writelane_b32 v213, vcc_hi, 4
	v_cmp_le_u32_e64 vcc, s18, v4
	s_bcnt1_i32_b64 s99, s[100:101]
	s_add_i32 s98, s98, s99
	v_writelane_b32 v212, s100, 5
	v_writelane_b32 v213, s101, 5
	v_cmp_le_u32_e64 s[100:101], s18, v8
	s_bcnt1_i32_b64 s99, vcc
	s_add_i32 s98, s98, s99
	v_writelane_b32 v212, vcc_lo, 6
	v_writelane_b32 v213, vcc_hi, 6
	s_nop 0
	s_bcnt1_i32_b64 s99, s[100:101]
	s_add_i32 s98, s98, s99
	v_writelane_b32 v212, s100, 7
	v_writelane_b32 v213, s101, 7
	s_cmpk_lg_i32 s98, 0x100
	s_cbranch_scc1 .Lsf_slow_13
	v_cmp_gt_u32_e64 s[100:101], 8, v0
	s_and_saveexec_b64 s[16:17], s[100:101]
	v_lshlrev_b32_e32 v0, 3, v0
	v_readlane_b32 s0, v236, 9
	v_readlane_b32 s1, v236, 10
	s_nop 4
	global_store_dwordx2 v0, v[212:213], s[0:1] offset:256
	s_branch .LBB0_1154

; DI void stage_acc(const f32x4 (&acc)[4][4], float* tile, int wm, int wn, int fr, int fq) {
; #pragma unroll
;   for (int mi = 0; mi < 4; ++mi)
; #pragma unroll
;     for (int ni = 0; ni < 4; ++ni)
; #pragma unroll
;       for (int j = 0; j < 4; ++j) tile[(wm * 64 + mi * 16 + fq * 4 + j) * EPS + wn * 64 + ni * 16 + fr] = acc[mi][ni][j];
; }
; DI void phaseA_tile(const P& p, int layer, int mt, int nt, char* lds) {
;     ...
;   const int wm = wave >> 1, wn = wave & 1;
;   const int seg = (col0 >> 6) + wn;
;   const int fr = lane & 15, fq = lane >> 4;
;   if (tid < 128) {
;     const float ss = (ssa.x + ssa.y + ssa.z + ssa.w) + (ssb.x + ssb.y + ssb.z + ssb.w) + (ssc.x + ssc.y + ssc.z + ssc.w) + (ssd.x + ssd.y + ssd.z + ssd.w);
;     rr[tid] = rsqrtf(ss * (1.f / 1024.f) + 1e-6f);
;   }
;   float* stg = (float*)lds;
;   stage_acc(acc, stg, wm, wn, fr, fq);
;   __syncthreads();
;   if (seg >= NSEG) return;
.LBB0_1196:
	s_or_b64 exec, exec, s[0:1]
	s_ashr_i32 s56, s4, 7
	s_bfe_u32 s0, s4, 0x10006
	v_bfe_u32 v88, v92, 4, 2
	v_and_b32_e32 v89, 15, v92
	s_lshl_b32 s11, s56, 6
	v_lshlrev_b32_e32 v127, 2, v88
	s_lshl_b32 s57, s0, 8
	s_lshl_b32 s20, s37, 1
	v_or_b32_e32 v66, s11, v127
	v_lshl_or_b32 v0, v89, 2, s57
	s_or_b32 s55, s0, s20
	v_mad_u64_u32 v[66:67], s[0:1], v66, s33, v[0:1]
	s_cmp_gt_i32 s55, 52
	s_cbranch_scc1 .Lstg_skip_a1
	v_add_u32_e32 v0, 0x400, v66
	ds_write2_b32 v66, v62, v58 offset1:16
	ds_write2_b32 v66, v63, v59 offset0:132 offset1:148
	ds_write2_b32 v0, v64, v60 offset0:8 offset1:24
	ds_write2_b32 v0, v65, v61 offset0:140 offset1:156
	ds_write2_b32 v66, v54, v50 offset0:32 offset1:48
	ds_write2_b32 v66, v55, v51 offset0:164 offset1:180
	ds_write2_b32 v0, v56, v52 offset0:40 offset1:56
	ds_write2_b32 v0, v57, v53 offset0:172 offset1:188
	v_add_u32_e32 v0, 0x2000, v66
	v_add_u32_e32 v67, 0x2400, v66
	ds_write2_b32 v0, v46, v42 offset0:64 offset1:80
	ds_write2_b32 v0, v47, v43 offset0:196 offset1:212
	ds_write2_b32 v67, v48, v44 offset0:72 offset1:88
	ds_write2_b32 v67, v49, v45 offset0:204 offset1:220
	ds_write2_b32 v0, v38, v34 offset0:96 offset1:112
	ds_write2_b32 v0, v39, v35 offset0:228 offset1:244
	ds_write2_b32 v67, v40, v36 offset0:104 offset1:120
	ds_write2_b32 v67, v41, v37 offset0:236 offset1:252
	v_add_u32_e32 v0, 0x4000, v66
	v_add_u32_e32 v67, 0x4400, v66
	v_add_u32_e32 v68, 0x4800, v66
	ds_write2_b32 v0, v30, v26 offset0:128 offset1:144
	ds_write2_b32 v67, v31, v27 offset0:4 offset1:20
	ds_write2_b32 v67, v32, v28 offset0:136 offset1:152
	ds_write2_b32 v68, v33, v29 offset0:12 offset1:28
	ds_write2_b32 v0, v22, v18 offset0:160 offset1:176
	ds_write2_b32 v67, v23, v19 offset0:36 offset1:52
	ds_write2_b32 v67, v24, v20 offset0:168 offset1:184
	ds_write2_b32 v68, v25, v21 offset0:44 offset1:60
	v_add_u32_e32 v0, 0x6000, v66
	v_add_u32_e32 v67, 0x6400, v66
	v_add_u32_e32 v66, 0x6800, v66
	ds_write2_b32 v0, v14, v10 offset0:192 offset1:208
	ds_write2_b32 v67, v15, v11 offset0:68 offset1:84
	ds_write2_b32 v67, v16, v12 offset0:200 offset1:216
	ds_write2_b32 v66, v17, v13 offset0:76 offset1:92
	ds_write2_b32 v0, v6, v2 offset0:224 offset1:240
	ds_write2_b32 v67, v7, v3 offset0:100 offset1:116
	ds_write2_b32 v67, v8, v4 offset0:232 offset1:248
	ds_write2_b32 v66, v9, v5 offset0:108 offset1:124
.Lstg_skip_a1:
	s_cmpk_gt_i32 s55, 0x54
	s_movk_i32 s5, 0x2000
	s_waitcnt lgkmcnt(0)
	s_barrier
	s_cbranch_scc1 .LBB0_1183
	v_and_b32_e32 v152, 63, v92
	s_cmp_lt_i32 s55, 53
	s_mov_b64 s[0:1], -1
	s_cbranch_scc0 .LBB0_1584
	s_cmpk_gt_i32 s36, 0xff
	s_cselect_b64 s[38:39], -1, 0
	s_cmpk_lt_i32 s36, 0x100
	s_cselect_b64 s[12:13], -1, 0
	s_and_b32 s0, s37, 0x7ffffffc
	s_cmp_lg_u32 s0, 16
	s_cbranch_scc1 .LBB0_1264
	v_lshlrev_b32_e32 v0, 2, v127
	v_lshl_add_u32 v0, s11, 2, v0
	s_add_i32 s16, s11, s10
	v_add_u32_e32 v80, 0x10800, v0
	s_ashr_i32 s0, s16, 8
	ds_read_b128 v[66:69], v80
	s_sub_i32 s14, s55, 32
	s_and_b32 s0, s0, -8
	s_or_b32 s0, s0, s14
	s_ashr_i32 s1, s0, 31
	s_lshl_b64 s[0:1], s[0:1], 18
	s_mov_b64 s[4:5], -1
	s_and_b64 vcc, exec, s[12:13]
	v_lshlrev_b32_e32 v70, 12, v89
	s_cbranch_vccz .LBB0_1201
	v_readlane_b32 s4, v240, 52
	s_add_u32 s4, s4, s0
	v_readlane_b32 s5, v240, 53
	s_addc_u32 s5, s5, s1
	v_mov_b32_e32 v71, v1
	v_lshl_add_u64 v[72:73], s[4:5], 0, v[70:71]
	s_mov_b64 s[4:5], 0
